# P1 row loop: forget-gate weight table held in 128 registers (loaded once), dot products as eight fma chains, wave sums via DPP and permlane swaps
# speedup vs baseline: 1.0043x; 1.0043x over previous
; #define GAS __attribute__((address_space(1)))
; template <int LO, int HI> __global__ void __launch_bounds__(NWAVES * 64, 2) fox_fwd(Args args) {
;     ...
;         const int m0 = gw * 16, b = m0 / T;
;         f32x4 gm[4], sh[4];
; #pragma unroll
;         for (int j = 0; j < 4; ++j) { const int col = P1COL(j); const f32x4 g = *(const f32x4*)(norm_g + col), scl = *(const f32x4*)(ADA + b * 3072 + 1024 + col);
;             gm[j] = g * (scl + 1.0f); sh[j] = *(const f32x4*)(ADA + b * 3072 + col); }
;         const float bfv = b_f[lane & 7]; f32x4 lsq[4];
; #pragma unroll
;         for (int k = 0; k < 4; ++k) lsq[k] = (f32x4){0.f, 0.f, 0.f, 0.f};
;         for (int r = 0; r < 16; ++r) { const int m = m0 + r;
;             const GAS float* xr = (const GAS float*)(x + (size_t)m * D);
;             f32x4 v[4]; float s2 = 0.f;
; #pragma unroll
;             for (int j = 0; j < 4; ++j) { v[j] = *(const GAS f32x4*)(xr + P1COL(j)); s2 += (v[j][0] * v[j][0] + v[j][1] * v[j][1]) + (v[j][2] * v[j][2] + v[j][3] * v[j][3]); }
;             const float rstd = 1.0f / sqrtf(wave_sum(s2) * (1.0f / D) + EPS);
.LBB0_130:
	s_or_b64 exec, exec, s[8:9]
	s_ashr_i32 s43, s15, 6
	s_lshl_b32 s8, s14, 3
	s_add_i32 s33, s8, s43
	s_ashr_i32 s8, s33, 31
	s_lshr_b32 s8, s8, 24
	s_add_i32 s8, s33, s8
	s_ashr_i32 s44, s8, 8
	s_mul_i32 s8, s44, 0xc00
	s_ashr_i32 s9, s8, 31
	s_lshl_b64 s[8:9], s[8:9], 2
	s_add_u32 s8, s26, s8
	s_addc_u32 s9, s27, s9
	s_add_u32 s10, s8, 0x1000
	s_addc_u32 s11, s9, 0
	s_lshl_b32 s28, s33, 4
	s_ashr_i32 s29, s28, 31
	s_lshl_b64 s[12:13], s[28:29], 12
	v_and_b32_e32 v1, 63, v34
	s_waitcnt lgkmcnt(0)
	s_add_u32 s30, s6, s12
	v_lshlrev_b32_e32 v54, 5, v1
	s_addc_u32 s31, s7, s13
	s_barrier
	global_load_dwordx4 v[26:29], v54, s[30:31]
	global_load_dwordx4 v[18:21], v54, s[30:31] offset:16
	global_load_dwordx4 v[22:25], v54, s[30:31] offset:2064
	global_load_dwordx4 v[30:33], v54, s[30:31] offset:2048
	global_load_dwordx4 v[38:41], v54, s[10:11] offset:16
	global_load_dwordx4 v[42:45], v54, s[10:11]
	v_mbcnt_lo_u32_b32 v3, -1, 0
	v_and_b32_e32 v2, 7, v34
	v_mbcnt_hi_u32_b32 v35, -1, v3
	v_or_b32_e32 v3, 0x800, v54
	v_lshlrev_b32_e32 v2, 2, v2
	global_load_dwordx4 v[46:49], v3, s[10:11] offset:16
	global_load_dwordx4 v[50:53], v3, s[10:11]
	global_load_dwordx4 v[58:61], v54, s[20:21] offset:16
	global_load_dwordx4 v[62:65], v54, s[20:21]
	global_load_dwordx4 v[74:77], v54, s[20:21] offset:2064
	global_load_dwordx4 v[78:81], v54, s[20:21] offset:2048
	global_load_dword v71, v2, s[4:5]
	v_xor_b32_e32 v83, 16, v35
	v_and_b32_e32 v68, 64, v35
	v_mov_b32_e32 v37, 0
	v_lshlrev_b32_e32 v36, 4, v1
	v_xor_b32_e32 v4, 1, v35
	v_add_u32_e32 v87, 64, v68
	s_mov_b64 s[12:13], 0x2000000
	v_xor_b32_e32 v5, 2, v35
	v_lshl_add_u64 v[2:3], s[26:27], 0, v[36:37]
	v_cmp_lt_i32_e32 vcc, v4, v87
	v_lshl_add_u64 v[56:57], v[2:3], 0, s[12:13]
	v_xor_b32_e32 v55, 4, v35
	v_cndmask_b32_e32 v2, v35, v4, vcc
	v_cmp_lt_i32_e32 vcc, v5, v87
	v_lshlrev_b32_e32 v165, 2, v2
	v_xor_b32_e32 v73, 8, v35
	v_cndmask_b32_e32 v88, v35, v5, vcc
	global_load_dwordx4 v[2:5], v54, s[8:9] offset:16
	global_load_dwordx4 v[6:9], v54, s[8:9]
	v_lshlrev_b32_e32 v169, 2, v88
	v_cmp_lt_i32_e32 vcc, v55, v87
	v_xor_b32_e32 v86, 32, v35
	v_mov_b32_e32 v69, 0x358637bd
	v_cndmask_b32_e32 v55, v35, v55, vcc
	v_lshlrev_b32_e32 v168, 2, v55
	v_cmp_lt_i32_e32 vcc, v73, v87
	s_mov_b32 s45, 0xf800000
	v_mov_b32_e32 v70, 0x260
	v_cndmask_b32_e32 v73, v35, v73, vcc
	v_lshlrev_b32_e32 v167, 2, v73
	v_cmp_lt_i32_e32 vcc, v83, v87
	s_lshl_b64 s[34:35], s[28:29], 11
	v_add_u32_e32 v72, 0, v54
	s_or_b32 s36, s28, 1
	s_ashr_i32 s37, s36, 31
	v_cmp_eq_u32_e64 s[10:11], 4, v1
	v_cmp_eq_u32_e64 s[12:13], 5, v1
	v_cmp_eq_u32_e64 s[14:15], 6, v1
	v_cmp_eq_u32_e64 s[16:17], 7, v1
	s_mov_b32 s29, 0xbfb8aa3b
	s_mov_b32 s46, 0x7f800000
	s_mov_b32 s47, 0x33800000
	s_movk_i32 s48, 0x2000
	s_mov_b64 s[38:39], 0x2800
	s_mov_b64 s[40:41], 0x800
	s_waitcnt vmcnt(14)
	v_pk_mul_f32 v[10:11], v[28:29], v[28:29]
	v_pk_mul_f32 v[12:13], v[26:27], v[26:27]
	s_waitcnt vmcnt(13)
	v_pk_mul_f32 v[14:15], v[20:21], v[20:21]
	v_pk_mul_f32 v[16:17], v[18:19], v[18:19]
	v_pk_mov_b32 v[84:85], v[12:13], v[10:11] op_sel:[1,0]
	v_mov_b32_e32 v13, v11
	v_pk_mov_b32 v[10:11], v[16:17], v[14:15] op_sel:[1,0]
	v_mov_b32_e32 v17, v15
	s_waitcnt vmcnt(11)
	v_mul_f32_e32 v66, v31, v31
	v_mul_f32_e32 v82, v33, v33
	v_pk_add_f32 v[12:13], v[84:85], v[12:13]
	v_pk_add_f32 v[10:11], v[10:11], v[16:17]
	v_mul_f32_e32 v89, v22, v22
	v_mul_f32_e32 v90, v23, v23
	v_mul_f32_e32 v91, v24, v24
	v_mul_f32_e32 v92, v25, v25
	v_pk_fma_f32 v[14:15], v[30:31], v[30:31], v[66:67] op_sel_hi:[1,1,0]
	v_pk_fma_f32 v[66:67], v[32:33], v[32:33], v[82:83] op_sel_hi:[1,1,0]
	v_pk_add_f32 v[12:13], v[12:13], v[12:13] op_sel:[0,1] op_sel_hi:[1,0]
	v_pk_add_f32 v[10:11], v[10:11], v[10:11] op_sel:[0,1] op_sel_hi:[1,0]
	v_mov_b32_e32 v15, v91
	v_mov_b32_e32 v67, v92
	v_mov_b32_e32 v13, v89
	v_mov_b32_e32 v11, v90
	v_pk_add_f32 v[14:15], v[14:15], v[66:67]
	v_pk_add_f32 v[10:11], v[12:13], v[10:11]
	v_cndmask_b32_e32 v82, v35, v83, vcc
	v_pk_add_f32 v[10:11], v[10:11], v[14:15]
	v_lshlrev_b32_e32 v166, 2, v82
	v_add_f32_e32 v66, v10, v11
	global_load_dwordx4 v[10:13], v54, s[8:9] offset:2064
	global_load_dwordx4 v[14:17], v54, s[8:9] offset:2048
	ds_bpermute_b32 v67, v165, v66
	s_waitcnt vmcnt(12)
	v_pk_add_f32 v[82:83], v[38:39], 1.0 op_sel_hi:[1,0]
	v_cmp_lt_i32_e32 vcc, v86, v87
	s_waitcnt vmcnt(11)
	v_pk_add_f32 v[44:45], v[44:45], 1.0 op_sel_hi:[1,0]
	s_waitcnt vmcnt(9)
	v_pk_add_f32 v[52:53], v[52:53], 1.0 op_sel_hi:[1,0]
	s_waitcnt lgkmcnt(0)
	v_add_f32_e32 v66, v66, v67
	ds_bpermute_b32 v67, v169, v66
	v_pk_add_f32 v[42:43], v[42:43], 1.0 op_sel_hi:[1,0]
	v_pk_add_f32 v[50:51], v[50:51], 1.0 op_sel_hi:[1,0]
	v_pk_add_f32 v[84:85], v[48:49], 1.0 op_sel_hi:[1,0]
	s_waitcnt vmcnt(5)
	v_pk_mul_f32 v[48:49], v[78:79], v[50:51]
	s_waitcnt lgkmcnt(0)
	v_add_f32_e32 v55, v66, v67
	ds_bpermute_b32 v66, v168, v55
	v_cndmask_b32_e32 v67, v35, v86, vcc
	v_lshlrev_b32_e32 v164, 2, v67
	v_pk_add_f32 v[86:87], v[46:47], 1.0 op_sel_hi:[1,0]
	v_pk_mul_f32 v[50:51], v[76:77], v[84:85]
	s_waitcnt lgkmcnt(0)
	v_add_f32_e32 v55, v55, v66
	ds_bpermute_b32 v73, v167, v55
	v_pk_add_f32 v[66:67], v[40:41], 1.0 op_sel_hi:[1,0]
	v_pk_mul_f32 v[40:41], v[62:63], v[42:43]
	v_pk_mul_f32 v[42:43], v[60:61], v[66:67]
	v_cmp_eq_u32_e64 s[8:9], 3, v1
	s_waitcnt lgkmcnt(0)
	v_add_f32_e32 v38, v55, v73
	ds_bpermute_b32 v39, v166, v38
	s_waitcnt lgkmcnt(0)
	v_add_f32_e32 v46, v38, v39
	ds_bpermute_b32 v47, v164, v46
	v_pk_mul_f32 v[38:39], v[64:65], v[44:45]
	v_pk_mul_f32 v[44:45], v[58:59], v[82:83]
	s_waitcnt lgkmcnt(0)
; #define GAS __attribute__((address_space(1)))
; #define LAS __attribute__((address_space(3)))
; __device__ __forceinline__ unsigned pk2(float lo, float hi) { return pg8::cvt_pk_bf16(lo, hi); }
; template <int LO, int HI> __global__ void __launch_bounds__(NWAVES * 64, 2) fox_fwd(Args args) {
;     ...
;             const float rstd = 1.0f / sqrtf(wave_sum(s2) * (1.0f / D) + EPS);
; #pragma unroll
;             for (int j = 0; j < 4; ++j) v[j] = v[j] * rstd * gm[j] + sh[j];
; #pragma unroll
;             for (int j = 0; j < 2; ++j) { v4u o; o.x = pk2(v[2 * j][0], v[2 * j][1]); o.y = pk2(v[2 * j][2], v[2 * j][3]); o.z = pk2(v[2 * j + 1][0], v[2 * j + 1][1]); o.w = pk2(v[2 * j + 1][2], v[2 * j + 1][3]);
;                 *(GAS v4u*)(HB + (size_t)m * D + 8 * lane + 512 * j) = o; }
;             float fl[8];
; #pragma unroll
;             for (int q = 0; q < 8; ++q) { float a = 0.f;
; #pragma unroll
;                 for (int j = 0; j < 4; ++j) { const f32x4 w = *(const LAS f32x4*)(wf + q * 1024 + P1COL(j)); a += (v[j][0] * w[0] + v[j][1] * w[1]) + (v[j][2] * w[2] + v[j][3] * w[3]); }
;                 fl[q] = wave_sum(a); }
	v_add_f32_e32 v46, v46, v47
	v_fmamk_f32 v46, v46, 0x3a800000, v69
	v_mul_f32_e32 v47, 0x4f800000, v46
	v_cmp_gt_f32_e32 vcc, s45, v46
	s_nop 1
	v_cndmask_b32_e32 v55, v46, v47, vcc
	v_sqrt_f32_e32 v58, v55
	v_pk_mul_f32 v[46:47], v[80:81], v[52:53]
	v_add_u32_e32 v52, -1, v58
	v_add_u32_e32 v53, 1, v58
	v_fma_f32 v59, -v52, v58, v55
	v_fma_f32 v60, -v53, v58, v55
	v_cmp_ge_f32_e64 s[4:5], 0, v59
	s_nop 1
	v_cndmask_b32_e64 v52, v58, v52, s[4:5]
	v_cmp_lt_f32_e64 s[4:5], 0, v60
	s_nop 1
	v_cndmask_b32_e64 v52, v52, v53, s[4:5]
	v_mul_f32_e32 v53, 0x37800000, v52
	v_cndmask_b32_e32 v52, v52, v53, vcc
	v_cmp_class_f32_e32 vcc, v55, v70
	s_nop 1
	v_cndmask_b32_e32 v55, v52, v55, vcc
	v_div_scale_f32 v58, s[4:5], v55, v55, 1.0
	v_rcp_f32_e32 v59, v58
	v_div_scale_f32 v60, vcc, 1.0, v55, 1.0
	v_pk_mul_f32 v[52:53], v[74:75], v[86:87]
	v_fma_f32 v61, -v58, v59, 1.0
	v_fmac_f32_e32 v59, v61, v59
	v_mul_f32_e32 v61, v60, v59
	v_fma_f32 v62, -v58, v61, v60
	v_fmac_f32_e32 v61, v62, v59
	v_fma_f32 v58, -v58, v61, v60
	v_div_fmas_f32 v58, v58, v59, v61
	v_div_fixup_f32 v64, v58, v55, 1.0
	v_pk_mul_f32 v[18:19], v[64:65], v[18:19] op_sel_hi:[0,1]
	v_pk_mul_f32 v[20:21], v[64:65], v[20:21] op_sel_hi:[0,1]
	s_waitcnt vmcnt(3)
	v_pk_fma_f32 v[60:61], v[42:43], v[20:21], v[4:5]
	v_pk_fma_f32 v[62:63], v[44:45], v[18:19], v[2:3]
	v_pk_mul_f32 v[18:19], v[64:65], v[30:31] op_sel_hi:[0,1]
	v_pk_mul_f32 v[20:21], v[64:65], v[32:33] op_sel_hi:[0,1]
	v_pk_mul_f32 v[58:59], v[64:65], v[26:27] op_sel_hi:[0,1]
	v_pk_mul_f32 v[26:27], v[64:65], v[28:29] op_sel_hi:[0,1]
	s_waitcnt vmcnt(0)
	v_pk_fma_f32 v[28:29], v[46:47], v[20:21], v[16:17]
	v_pk_fma_f32 v[30:31], v[48:49], v[18:19], v[14:15]
	v_pk_mul_f32 v[18:19], v[64:65], v[22:23] op_sel_hi:[0,1]
	v_pk_mul_f32 v[20:21], v[64:65], v[24:25] op_sel_hi:[0,1]
	v_pk_fma_f32 v[26:27], v[38:39], v[26:27], v[8:9]
	v_pk_fma_f32 v[58:59], v[40:41], v[58:59], v[6:7]
	v_pk_fma_f32 v[22:23], v[50:51], v[20:21], v[12:13]
	v_pk_fma_f32 v[24:25], v[52:53], v[18:19], v[10:11]
	v_lshl_add_u64 v[32:33], v[56:57], 0, s[34:35]
	v_cvt_pk_bf16_f32 v18, v58, v59
	v_cvt_pk_bf16_f32 v19, v26, v27
	v_cvt_pk_bf16_f32 v20, v62, v63
	v_cvt_pk_bf16_f32 v21, v60, v61
	global_store_dwordx4 v[32:33], v[18:21], off
	s_lshl_b64 s[4:5], s[36:37], 12
	s_add_u32 s4, s6, s4
	v_cvt_pk_bf16_f32 v18, v30, v31
	v_cvt_pk_bf16_f32 v19, v28, v29
	v_cvt_pk_bf16_f32 v20, v24, v25
	v_cvt_pk_bf16_f32 v21, v22, v23
	ds_read_b128 v[64:67], v72
	ds_read_b128 v[74:77], v72 offset:16
	global_store_dwordx4 v[32:33], v[18:21], off offset:1024
	ds_read_b128 v[18:21], v72 offset:12288
	s_addc_u32 s5, s7, s5
	s_waitcnt lgkmcnt(2)
	v_mul_f32_e32 v55, v59, v65
	v_fmac_f32_e32 v55, v58, v64
	v_mul_f32_e32 v64, v27, v67
	v_fmac_f32_e32 v64, v26, v66
	v_add_f32_e32 v55, v55, v64
	ds_read_b128 v[64:67], v72 offset:2048
	s_waitcnt lgkmcnt(2)
	v_mul_f32_e32 v73, v63, v75
	v_fmac_f32_e32 v73, v62, v74
	v_mul_f32_e32 v74, v61, v77
	v_fmac_f32_e32 v74, v60, v76
	v_add_f32_e32 v73, v73, v74
	ds_read_b128 v[74:77], v72 offset:2064
	s_waitcnt lgkmcnt(1)
	v_mul_f32_e32 v65, v31, v65
	v_fmac_f32_e32 v65, v30, v64
	v_mul_f32_e32 v64, v29, v67
	v_add_f32_e32 v55, 0, v55
	v_fmac_f32_e32 v64, v28, v66
	v_add_f32_e32 v55, v55, v73
	v_add_f32_e32 v64, v65, v64
	v_add_f32_e32 v55, v55, v64
	s_waitcnt lgkmcnt(0)
	v_mul_f32_e32 v64, v25, v75
	v_mul_f32_e32 v65, v23, v77
	v_fmac_f32_e32 v64, v24, v74
	v_fmac_f32_e32 v65, v22, v76
	v_add_f32_e32 v64, v64, v65
	v_add_f32_e32 v55, v55, v64
	ds_bpermute_b32 v64, v165, v55
	ds_read_b128 v[74:77], v72 offset:4112
	v_cmp_eq_u32_e64 s[6:7], 2, v1
	s_waitcnt lgkmcnt(1)
	v_add_f32_e32 v55, v55, v64
	ds_bpermute_b32 v64, v169, v55
	s_waitcnt lgkmcnt(1)
	v_mul_f32_e32 v75, v63, v75
	v_fmac_f32_e32 v75, v62, v74
	v_mul_f32_e32 v74, v61, v77
	v_fmac_f32_e32 v74, v60, v76
	s_waitcnt lgkmcnt(0)
	v_add_f32_e32 v55, v55, v64
	ds_read_b128 v[64:67], v72 offset:4096
	v_add_f32_e32 v74, v75, v74
	ds_bpermute_b32 v73, v168, v55
	s_waitcnt lgkmcnt(1)
	v_mul_f32_e32 v65, v59, v65
	v_fmac_f32_e32 v65, v58, v64
	v_mul_f32_e32 v64, v27, v67
	v_fmac_f32_e32 v64, v26, v66
	v_add_f32_e32 v64, v65, v64
	v_add_f32_e32 v78, 0, v64
	ds_read_b128 v[64:67], v72 offset:6144
	v_add_f32_e32 v78, v78, v74
	ds_read_b128 v[74:77], v72 offset:6160
	s_waitcnt lgkmcnt(2)
	v_add_f32_e32 v55, v55, v73
	ds_bpermute_b32 v73, v167, v55
	s_waitcnt lgkmcnt(2)
	v_mul_f32_e32 v65, v31, v65
	v_fmac_f32_e32 v65, v30, v64
	v_mul_f32_e32 v64, v29, v67
	v_fmac_f32_e32 v64, v28, v66
	v_add_f32_e32 v64, v65, v64
	s_waitcnt lgkmcnt(1)
	v_mul_f32_e32 v65, v25, v75
	v_mul_f32_e32 v66, v23, v77
	v_fmac_f32_e32 v65, v24, v74
	v_fmac_f32_e32 v66, v22, v76
	v_add_f32_e32 v64, v78, v64
	v_add_f32_e32 v65, v65, v66
	v_add_f32_e32 v64, v64, v65
	ds_bpermute_b32 v65, v165, v64
	s_waitcnt lgkmcnt(1)
	v_add_f32_e32 v55, v55, v73
	ds_bpermute_b32 v74, v166, v55
	v_lshlrev_b32_e32 v73, 3, v1
	s_waitcnt lgkmcnt(1)
	v_add_f32_e32 v75, v64, v65
	ds_bpermute_b32 v76, v169, v75
	ds_read_b128 v[64:67], v72 offset:8192
	s_waitcnt lgkmcnt(2)
	v_add_f32_e32 v55, v55, v74
	s_waitcnt lgkmcnt(1)
	v_add_f32_e32 v78, v75, v76
	ds_read_b128 v[74:77], v72 offset:8208
	s_waitcnt lgkmcnt(1)
	v_mul_f32_e32 v65, v59, v65
	v_fmac_f32_e32 v65, v58, v64
	v_mul_f32_e32 v64, v27, v67
	v_fmac_f32_e32 v64, v26, v66
	v_add_f32_e32 v64, v65, v64
	s_waitcnt lgkmcnt(0)
	v_mul_f32_e32 v75, v63, v75
	v_add_f32_e32 v80, 0, v64
	v_fmac_f32_e32 v75, v62, v74
	v_mul_f32_e32 v74, v61, v77
	ds_read_b128 v[64:67], v72 offset:10240
	v_fmac_f32_e32 v74, v60, v76
	v_add_f32_e32 v74, v75, v74
	v_add_f32_e32 v80, v80, v74
	ds_read_b128 v[74:77], v72 offset:10256
	s_waitcnt lgkmcnt(1)
; #define LAS __attribute__((address_space(3)))
; template <int LO, int HI> __global__ void __launch_bounds__(NWAVES * 64, 2) fox_fwd(Args args) {
;     ...
;             for (int q = 0; q < 8; ++q) { float a = 0.f;
; #pragma unroll
;                 for (int j = 0; j < 4; ++j) { const f32x4 w = *(const LAS f32x4*)(wf + q * 1024 + P1COL(j)); a += (v[j][0] * w[0] + v[j][1] * w[1]) + (v[j][2] * w[2] + v[j][3] * w[3]); }
;                 fl[q] = wave_sum(a); }
	v_mul_f32_e32 v65, v31, v65
	ds_bpermute_b32 v79, v168, v78
	v_fmac_f32_e32 v65, v30, v64
	v_mul_f32_e32 v64, v29, v67
	v_fmac_f32_e32 v64, v28, v66
	v_add_f32_e32 v64, v65, v64
	s_waitcnt lgkmcnt(1)
	v_mul_f32_e32 v65, v25, v75
	v_mul_f32_e32 v66, v23, v77
	v_fmac_f32_e32 v65, v24, v74
	v_fmac_f32_e32 v66, v22, v76
	v_add_f32_e32 v64, v80, v64
	v_add_f32_e32 v65, v65, v66
	v_add_f32_e32 v64, v64, v65
	s_waitcnt lgkmcnt(0)
	v_add_f32_e32 v67, v78, v79
	ds_bpermute_b32 v65, v165, v64
	ds_bpermute_b32 v66, v164, v55
	ds_bpermute_b32 v74, v167, v67
	s_waitcnt lgkmcnt(2)
	v_add_f32_e32 v32, v64, v65
	s_waitcnt lgkmcnt(1)
	v_add_f32_e32 v55, v55, v66
	s_waitcnt lgkmcnt(0)
	v_add_f32_e32 v74, v67, v74
	ds_read_b128 v[64:67], v72 offset:12304
	v_mul_f32_e32 v19, v59, v19
	v_fmac_f32_e32 v19, v58, v18
	v_mul_f32_e32 v18, v27, v21
	v_fmac_f32_e32 v18, v26, v20
	v_add_f32_e32 v18, v19, v18
	s_waitcnt lgkmcnt(0)
	v_mul_f32_e32 v65, v63, v65
	v_add_f32_e32 v76, 0, v18
	v_fmac_f32_e32 v65, v62, v64
	v_mul_f32_e32 v64, v61, v67
	ds_read_b128 v[18:21], v72 offset:14336
	v_fmac_f32_e32 v64, v60, v66
	v_add_f32_e32 v64, v65, v64
	v_add_f32_e32 v76, v76, v64
	ds_read_b128 v[64:67], v72 offset:14352
	s_waitcnt lgkmcnt(1)
	v_mul_f32_e32 v19, v31, v19
	v_fmac_f32_e32 v19, v30, v18
	v_mul_f32_e32 v18, v29, v21
	v_fmac_f32_e32 v18, v28, v20
	v_add_f32_e32 v18, v19, v18
	s_waitcnt lgkmcnt(0)
	v_mul_f32_e32 v19, v25, v65
	v_mul_f32_e32 v20, v23, v67
	v_fmac_f32_e32 v19, v24, v64
	v_fmac_f32_e32 v20, v22, v66
	v_add_f32_e32 v18, v76, v18
	v_add_f32_e32 v19, v19, v20
	v_add_f32_e32 v64, v18, v19
	ds_bpermute_b32 v75, v166, v74
	ds_bpermute_b32 v65, v165, v64
	ds_read_b128 v[18:21], v72 offset:16384
	ds_bpermute_b32 v33, v169, v32
	s_waitcnt lgkmcnt(3)
	v_add_f32_e32 v74, v74, v75
	s_waitcnt lgkmcnt(2)
	v_add_f32_e32 v75, v64, v65
	ds_read_b128 v[64:67], v72 offset:16400
	s_waitcnt lgkmcnt(2)
	v_mul_f32_e32 v19, v59, v19
	v_fmac_f32_e32 v19, v58, v18
	v_mul_f32_e32 v18, v27, v21
	v_fmac_f32_e32 v18, v26, v20
	v_add_f32_e32 v18, v19, v18
	s_waitcnt lgkmcnt(0)
	v_mul_f32_e32 v65, v63, v65
	v_add_f32_e32 v77, 0, v18
	v_fmac_f32_e32 v65, v62, v64
	v_mul_f32_e32 v64, v61, v67
	ds_read_b128 v[18:21], v72 offset:18432
	v_fmac_f32_e32 v64, v60, v66
	v_add_f32_e32 v64, v65, v64
	v_add_f32_e32 v32, v32, v33
	v_add_f32_e32 v77, v77, v64
	ds_read_b128 v[64:67], v72 offset:18448
	ds_bpermute_b32 v33, v168, v32
	s_waitcnt lgkmcnt(2)
	v_mul_f32_e32 v19, v31, v19
	v_fmac_f32_e32 v19, v30, v18
	v_mul_f32_e32 v18, v29, v21
	v_fmac_f32_e32 v18, v28, v20
	v_add_f32_e32 v18, v19, v18
	s_waitcnt lgkmcnt(1)
	v_mul_f32_e32 v19, v25, v65
	v_mul_f32_e32 v20, v23, v67
	s_waitcnt lgkmcnt(0)
	v_add_f32_e32 v32, v32, v33
	ds_bpermute_b32 v76, v169, v75
	v_fmac_f32_e32 v19, v24, v64
	v_fmac_f32_e32 v20, v22, v66
	ds_bpermute_b32 v33, v167, v32
	v_add_f32_e32 v18, v77, v18
	v_add_f32_e32 v19, v19, v20
	v_add_f32_e32 v18, v18, v19
	ds_bpermute_b32 v19, v165, v18
	s_waitcnt lgkmcnt(2)
	v_add_f32_e32 v21, v75, v76
	s_waitcnt lgkmcnt(1)
	v_add_f32_e32 v20, v32, v33
	ds_bpermute_b32 v32, v168, v21
	ds_bpermute_b32 v33, v166, v20
	s_waitcnt lgkmcnt(2)
	v_add_f32_e32 v18, v18, v19
	ds_bpermute_b32 v19, v169, v18
	ds_bpermute_b32 v64, v164, v74
	s_waitcnt lgkmcnt(3)
	v_add_f32_e32 v21, v21, v32
	ds_bpermute_b32 v32, v167, v21
	s_waitcnt lgkmcnt(3)
	v_add_f32_e32 v20, v20, v33
	s_waitcnt lgkmcnt(2)
	v_add_f32_e32 v18, v18, v19
	ds_bpermute_b32 v19, v168, v18
	ds_bpermute_b32 v33, v164, v20
	s_waitcnt lgkmcnt(2)
	v_add_f32_e32 v21, v21, v32
	ds_bpermute_b32 v32, v166, v21
	v_add_f32_e32 v74, v74, v64
	s_waitcnt lgkmcnt(2)
	v_add_f32_e32 v64, v18, v19
	ds_bpermute_b32 v65, v167, v64
	s_waitcnt lgkmcnt(2)
	v_add_f32_e32 v75, v20, v33
	s_waitcnt lgkmcnt(1)
	v_add_f32_e32 v32, v21, v32
	ds_read_b128 v[18:21], v72 offset:20480
	ds_bpermute_b32 v33, v164, v32
	s_waitcnt lgkmcnt(2)
	v_add_f32_e32 v76, v64, v65
	ds_read_b128 v[64:67], v72 offset:20496
	ds_bpermute_b32 v77, v166, v76
	s_waitcnt lgkmcnt(3)
	v_mul_f32_e32 v19, v59, v19
	v_fmac_f32_e32 v19, v58, v18
	v_mul_f32_e32 v18, v27, v21
	v_fmac_f32_e32 v18, v26, v20
	v_add_f32_e32 v18, v19, v18
	s_waitcnt lgkmcnt(1)
	v_mul_f32_e32 v65, v63, v65
	v_add_f32_e32 v78, 0, v18
	v_fmac_f32_e32 v65, v62, v64
	v_mul_f32_e32 v64, v61, v67
	ds_read_b128 v[18:21], v72 offset:22528
	v_fmac_f32_e32 v64, v60, v66
	v_add_f32_e32 v64, v65, v64
	v_add_f32_e32 v78, v78, v64
	ds_read_b128 v[64:67], v72 offset:22544
	s_waitcnt lgkmcnt(1)
	v_mul_f32_e32 v19, v31, v19
	v_fmac_f32_e32 v19, v30, v18
	v_mul_f32_e32 v18, v29, v21
	v_fmac_f32_e32 v18, v28, v20
	v_add_f32_e32 v18, v19, v18
	s_waitcnt lgkmcnt(0)
	v_mul_f32_e32 v19, v25, v65
	v_mul_f32_e32 v20, v23, v67
	v_fmac_f32_e32 v19, v24, v64
	v_fmac_f32_e32 v20, v22, v66
	v_add_f32_e32 v18, v78, v18
	v_add_f32_e32 v19, v19, v20
	v_add_f32_e32 v64, v18, v19
	ds_bpermute_b32 v65, v165, v64
	ds_read_b128 v[18:21], v72 offset:24576
	v_add_f32_e32 v92, v32, v33
	v_add_f32_e32 v93, v76, v77
	ds_bpermute_b32 v94, v164, v93
	s_waitcnt lgkmcnt(2)
	v_add_f32_e32 v95, v64, v65
	ds_read_b128 v[64:67], v72 offset:24592
	s_waitcnt lgkmcnt(2)
	v_pk_mul_f32 v[18:19], v[58:59], v[18:19]
	v_pk_mul_f32 v[20:21], v[26:27], v[20:21]
	ds_bpermute_b32 v96, v169, v95
	v_pk_mov_b32 v[32:33], v[18:19], v[20:21] op_sel:[1,0]
	v_mov_b32_e32 v19, v21
	v_pk_add_f32 v[18:19], v[32:33], v[18:19]
	s_waitcnt lgkmcnt(1)
	v_pk_mul_f32 v[64:65], v[62:63], v[64:65]
	v_add_f32_e32 v18, v18, v19
	v_add_f32_e32 v32, 0, v18
	ds_read_b128 v[18:21], v72 offset:26624
	ds_read_b128 v[76:79], v72 offset:26640
	global_load_dwordx4 v[80:83], v54, s[4:5] offset:16
	global_load_dwordx4 v[84:87], v54, s[4:5]
	v_pk_mul_f32 v[66:67], v[60:61], v[66:67]
	s_waitcnt lgkmcnt(0)
; #define GAS __attribute__((address_space(1)))
; #define LAS __attribute__((address_space(3)))
; __device__ __forceinline__ unsigned pk2(float lo, float hi) { return pg8::cvt_pk_bf16(lo, hi); }
; template <int LO, int HI> __global__ void __launch_bounds__(NWAVES * 64, 2) fox_fwd(Args args) {
;     ...
;         for (int r = 0; r < 16; ++r) { const int m = m0 + r;
;             const GAS float* xr = (const GAS float*)(x + (size_t)m * D);
;             f32x4 v[4]; float s2 = 0.f;
; #pragma unroll
;             for (int j = 0; j < 4; ++j) { v[j] = *(const GAS f32x4*)(xr + P1COL(j)); s2 += (v[j][0] * v[j][0] + v[j][1] * v[j][1]) + (v[j][2] * v[j][2] + v[j][3] * v[j][3]); }
;             const float rstd = 1.0f / sqrtf(wave_sum(s2) * (1.0f / D) + EPS);
; #pragma unroll
;             for (int j = 0; j < 4; ++j) v[j] = v[j] * rstd * gm[j] + sh[j];
; #pragma unroll
;             for (int j = 0; j < 2; ++j) { v4u o; o.x = pk2(v[2 * j][0], v[2 * j][1]); o.y = pk2(v[2 * j][2], v[2 * j][3]); o.z = pk2(v[2 * j + 1][0], v[2 * j + 1][1]); o.w = pk2(v[2 * j + 1][2], v[2 * j + 1][3]);
;                 *(GAS v4u*)(HB + (size_t)m * D + 8 * lane + 512 * j) = o; }
;             float fl[8];
; #pragma unroll
;             for (int q = 0; q < 8; ++q) { float a = 0.f;
; #pragma unroll
;                 for (int j = 0; j < 4; ++j) { const f32x4 w = *(const LAS f32x4*)(wf + q * 1024 + P1COL(j)); a += (v[j][0] * w[0] + v[j][1] * w[1]) + (v[j][2] * w[2] + v[j][3] * w[3]); }
;                 fl[q] = wave_sum(a); }
;             float mine = fl[0];
; #pragma unroll
;             for (int q = 1; q < 8; ++q) mine = (lane == q) ? fl[q] : mine;
;             { const float z = mine + bfv; const float ls = fminf(z, 0.f) - log1pf(__expf(-fabsf(z)));
	v_mul_f32_e32 v33, v24, v76
	v_pk_mov_b32 v[88:89], v[64:65], v[66:67] op_sel:[1,0]
	v_mov_b32_e32 v65, v67
	v_pk_add_f32 v[64:65], v[88:89], v[64:65]
	v_mul_f32_e32 v66, v25, v77
	v_mul_f32_e32 v67, v22, v78
	v_mul_f32_e32 v97, v23, v79
	global_load_dwordx4 v[76:79], v54, s[4:5] offset:2048
	global_load_dwordx4 v[88:91], v54, s[4:5] offset:2064
	v_pk_add_f32 v[64:65], v[64:65], v[64:65] op_sel:[0,1] op_sel_hi:[1,0]
	v_cmp_eq_u32_e64 s[4:5], 1, v1
	v_mov_b32_e32 v65, v66
	v_pk_add_f32 v[32:33], v[32:33], v[64:65]
	v_mul_f32_e32 v64, v31, v19
	v_pk_fma_f32 v[18:19], v[30:31], v[18:19], v[64:65] op_sel_hi:[1,1,0]
	v_mul_f32_e32 v64, v29, v21
	v_pk_fma_f32 v[20:21], v[28:29], v[20:21], v[64:65] op_sel_hi:[1,1,0]
	v_mov_b32_e32 v19, v67
	v_mov_b32_e32 v21, v97
	v_pk_add_f32 v[64:65], v[18:19], v[20:21]
	ds_read_b128 v[18:21], v72 offset:28672
	v_pk_add_f32 v[32:33], v[32:33], v[64:65]
	ds_read_b128 v[64:67], v72 offset:28688
	v_add_f32_e32 v97, v32, v33
	ds_bpermute_b32 v98, v165, v97
	s_waitcnt lgkmcnt(2)
	v_pk_mul_f32 v[18:19], v[58:59], v[18:19]
	v_pk_mul_f32 v[20:21], v[26:27], v[20:21]
	s_waitcnt lgkmcnt(1)
	v_pk_mul_f32 v[32:33], v[62:63], v[64:65]
	v_pk_mov_b32 v[26:27], v[18:19], v[20:21] op_sel:[1,0]
	v_mov_b32_e32 v19, v21
	v_pk_add_f32 v[18:19], v[26:27], v[18:19]
	v_pk_mul_f32 v[58:59], v[60:61], v[66:67]
	v_add_f32_e32 v18, v18, v19
	v_add_f32_e32 v26, 0, v18
	ds_read_b128 v[18:21], v72 offset:30720
	ds_read_b128 v[62:65], v72 offset:30736
	v_pk_mov_b32 v[60:61], v[32:33], v[58:59] op_sel:[1,0]
	v_mov_b32_e32 v33, v59
	v_pk_add_f32 v[32:33], v[60:61], v[32:33]
	s_waitcnt lgkmcnt(0)
	v_mul_f32_e32 v27, v24, v62
	v_mul_f32_e32 v24, v25, v63
	v_mul_f32_e32 v25, v22, v64
	v_mul_f32_e32 v58, v23, v65
	v_pk_add_f32 v[22:23], v[32:33], v[32:33] op_sel:[0,1] op_sel_hi:[1,0]
	s_nop 0
	v_mov_b32_e32 v23, v24
	v_mul_f32_e32 v24, v31, v19
	v_pk_fma_f32 v[18:19], v[30:31], v[18:19], v[24:25] op_sel_hi:[1,1,0]
	v_mul_f32_e32 v24, v29, v21
	v_pk_fma_f32 v[20:21], v[28:29], v[20:21], v[24:25] op_sel_hi:[1,1,0]
	v_mov_b32_e32 v19, v25
	v_mov_b32_e32 v21, v58
	v_pk_add_f32 v[22:23], v[26:27], v[22:23]
	v_pk_add_f32 v[18:19], v[18:19], v[20:21]
	v_add_f32_e32 v20, v95, v96
	v_pk_add_f32 v[18:19], v[22:23], v[18:19]
	ds_bpermute_b32 v21, v168, v20
	v_add_f32_e32 v18, v18, v19
	ds_bpermute_b32 v19, v165, v18
	v_add_f32_e32 v22, v97, v98
	ds_bpermute_b32 v23, v169, v22
	s_waitcnt lgkmcnt(2)
	v_add_f32_e32 v20, v20, v21
	ds_bpermute_b32 v21, v167, v20
	s_waitcnt lgkmcnt(2)
	v_add_f32_e32 v18, v18, v19
	ds_bpermute_b32 v19, v169, v18
	s_waitcnt lgkmcnt(2)
	v_add_f32_e32 v22, v22, v23
	ds_bpermute_b32 v23, v168, v22
	s_waitcnt lgkmcnt(2)
	v_add_f32_e32 v20, v20, v21
	ds_bpermute_b32 v21, v166, v20
	s_waitcnt lgkmcnt(2)
	v_add_f32_e32 v18, v18, v19
	ds_bpermute_b32 v19, v168, v18
	s_waitcnt lgkmcnt(2)
	v_add_f32_e32 v22, v22, v23
	ds_bpermute_b32 v23, v167, v22
	s_waitcnt lgkmcnt(2)
	v_add_f32_e32 v26, v20, v21
	ds_bpermute_b32 v27, v164, v26
	s_waitcnt lgkmcnt(2)
	v_add_f32_e32 v18, v18, v19
	ds_bpermute_b32 v19, v167, v18
	s_waitcnt vmcnt(2)
	v_pk_mul_f32 v[20:21], v[84:85], v[84:85]
	s_waitcnt lgkmcnt(2)
	v_add_f32_e32 v28, v22, v23
	ds_bpermute_b32 v29, v166, v28
	s_waitcnt lgkmcnt(1)
	v_add_f32_e32 v30, v18, v19
	v_pk_mul_f32 v[18:19], v[86:87], v[86:87]
	ds_bpermute_b32 v31, v166, v30
	v_pk_mov_b32 v[22:23], v[20:21], v[18:19] op_sel:[1,0]
	v_mov_b32_e32 v21, v19
	v_pk_add_f32 v[18:19], v[22:23], v[20:21]
	v_pk_mul_f32 v[20:21], v[82:83], v[82:83]
	v_pk_mul_f32 v[22:23], v[80:81], v[80:81]
	v_pk_add_f32 v[18:19], v[18:19], v[18:19] op_sel:[0,1] op_sel_hi:[1,0]
	v_pk_mov_b32 v[24:25], v[22:23], v[20:21] op_sel:[1,0]
	v_mov_b32_e32 v23, v21
	v_pk_add_f32 v[20:21], v[24:25], v[22:23]
	s_waitcnt vmcnt(0)
	v_mul_f32_e32 v22, v88, v88
	v_mul_f32_e32 v23, v89, v89
	v_pk_add_f32 v[20:21], v[20:21], v[20:21] op_sel:[0,1] op_sel_hi:[1,0]
	v_mov_b32_e32 v19, v22
	v_mov_b32_e32 v21, v23
	v_pk_add_f32 v[18:19], v[18:19], v[20:21]
	v_mul_f32_e32 v20, v77, v77
	v_mul_f32_e32 v22, v79, v79
	v_mul_f32_e32 v24, v90, v90
	v_mul_f32_e32 v25, v91, v91
	v_pk_fma_f32 v[20:21], v[76:77], v[76:77], v[20:21] op_sel_hi:[1,1,0]
	v_pk_fma_f32 v[22:23], v[78:79], v[78:79], v[22:23] op_sel_hi:[1,1,0]
	v_mov_b32_e32 v21, v24
	v_mov_b32_e32 v23, v25
	v_pk_add_f32 v[20:21], v[20:21], v[22:23]
	s_waitcnt lgkmcnt(0)
	v_add_f32_e32 v22, v30, v31
	v_pk_add_f32 v[18:19], v[18:19], v[20:21]
	v_add_f32_e32 v20, v28, v29
	v_add_f32_e32 v18, v18, v19
	ds_bpermute_b32 v19, v165, v18
	ds_bpermute_b32 v21, v164, v20
	ds_bpermute_b32 v23, v164, v22
	v_add_f32_e32 v24, v93, v94
	v_add_f32_e32 v25, v26, v27
	s_waitcnt lgkmcnt(2)
	v_add_f32_e32 v18, v18, v19
	ds_bpermute_b32 v19, v169, v18
	s_waitcnt lgkmcnt(2)
	v_add_f32_e32 v20, v20, v21
	s_waitcnt lgkmcnt(1)
	v_add_f32_e32 v21, v22, v23
	v_cndmask_b32_e64 v22, v55, v74, s[4:5]
	v_cndmask_b32_e64 v22, v22, v75, s[6:7]
	s_waitcnt lgkmcnt(0)
	v_add_f32_e32 v18, v18, v19
	ds_bpermute_b32 v19, v168, v18
	v_cndmask_b32_e64 v22, v22, v92, s[8:9]
	v_cndmask_b32_e64 v22, v22, v24, s[10:11]
	v_cndmask_b32_e64 v22, v22, v25, s[12:13]
	v_cndmask_b32_e64 v20, v22, v20, s[14:15]
	s_waitcnt lgkmcnt(0)
	v_add_f32_e32 v18, v18, v19
	ds_bpermute_b32 v19, v167, v18
	v_cndmask_b32_e64 v20, v20, v21, s[16:17]
	v_add_f32_e32 v20, v71, v20
	v_min_f32_e32 v22, 0, v20
	v_mul_f32_e64 v20, |v20|, s29
	s_waitcnt lgkmcnt(0)
	v_add_f32_e32 v18, v18, v19
	ds_bpermute_b32 v19, v166, v18
	v_exp_f32_e32 v55, v20
	s_waitcnt lgkmcnt(0)
	v_add_f32_e32 v18, v18, v19
	ds_bpermute_b32 v19, v164, v18
	v_add_f32_e32 v92, 1.0, v55
	v_add_f32_e32 v23, -1.0, v92
	v_sub_f32_e32 v26, v23, v92
	v_add_f32_e32 v26, 1.0, v26
	s_waitcnt lgkmcnt(0)
; #define GAS __attribute__((address_space(1)))
; #define LAS __attribute__((address_space(3)))
; __device__ __forceinline__ unsigned pk2(float lo, float hi) { return pg8::cvt_pk_bf16(lo, hi); }
; template <int LO, int HI> __global__ void __launch_bounds__(NWAVES * 64, 2) fox_fwd(Args args) {
;     ...
;             const float rstd = 1.0f / sqrtf(wave_sum(s2) * (1.0f / D) + EPS);
; #pragma unroll
;             for (int j = 0; j < 4; ++j) v[j] = v[j] * rstd * gm[j] + sh[j];
; #pragma unroll
;             for (int j = 0; j < 2; ++j) { v4u o; o.x = pk2(v[2 * j][0], v[2 * j][1]); o.y = pk2(v[2 * j][2], v[2 * j][3]); o.z = pk2(v[2 * j + 1][0], v[2 * j + 1][1]); o.w = pk2(v[2 * j + 1][2], v[2 * j + 1][3]);
;                 *(GAS v4u*)(HB + (size_t)m * D + 8 * lane + 512 * j) = o; }
;             float fl[8];
; #pragma unroll
;             for (int q = 0; q < 8; ++q) { float a = 0.f;
; #pragma unroll
;                 for (int j = 0; j < 4; ++j) { const f32x4 w = *(const LAS f32x4*)(wf + q * 1024 + P1COL(j)); a += (v[j][0] * w[0] + v[j][1] * w[1]) + (v[j][2] * w[2] + v[j][3] * w[3]); }
;                 fl[q] = wave_sum(a); }
;             float mine = fl[0];
; #pragma unroll
;             for (int q = 1; q < 8; ++q) mine = (lane == q) ? fl[q] : mine;
;             { const float z = mine + bfv; const float ls = fminf(z, 0.f) - log1pf(__expf(-fabsf(z)));
	v_add_f32_e32 v18, v18, v19
	v_fmamk_f32 v18, v18, 0x3a800000, v69
	v_mul_f32_e32 v19, 0x4f800000, v18
	v_cmp_gt_f32_e32 vcc, s45, v18
	v_sub_f32_e32 v23, v55, v23
	v_add_f32_e32 v23, v23, v26
	v_cndmask_b32_e32 v18, v18, v19, vcc
	v_sqrt_f32_e32 v19, v18
	s_nop 0
	v_add_u32_e32 v20, -1, v19
	v_fma_f32 v21, -v20, v19, v18
	v_cmp_ge_f32_e64 s[20:21], 0, v21
	v_add_u32_e32 v21, 1, v19
	s_nop 0
	v_cndmask_b32_e64 v20, v19, v20, s[20:21]
	v_fma_f32 v19, -v21, v19, v18
	v_cmp_lt_f32_e64 s[20:21], 0, v19
	s_nop 1
	v_cndmask_b32_e64 v19, v20, v21, s[20:21]
	v_mul_f32_e32 v20, 0x37800000, v19
	v_cndmask_b32_e32 v19, v19, v20, vcc
	v_cmp_class_f32_e32 vcc, v18, v70
	s_nop 1
	v_cndmask_b32_e32 v18, v19, v18, vcc
	v_div_scale_f32 v19, s[20:21], v18, v18, 1.0
	v_rcp_f32_e32 v20, v19
	s_lshl_b64 s[20:21], s[36:37], 11
	s_mov_b32 s37, 0x3f2aaaab
	s_mov_b32 s36, 0x3f317218
	v_fma_f32 v21, -v19, v20, 1.0
	v_fmac_f32_e32 v20, v21, v20
	v_div_scale_f32 v21, vcc, 1.0, v18, 1.0
	v_mul_f32_e32 v24, v21, v20
	v_fma_f32 v25, -v19, v24, v21
	v_fmac_f32_e32 v24, v25, v20
	v_fma_f32 v19, -v19, v24, v21
	v_div_fmas_f32 v19, v19, v20, v24
	v_div_fixup_f32 v18, v19, v18, 1.0
	v_pk_mul_f32 v[20:21], v[18:19], v[84:85] op_sel_hi:[0,1]
	v_pk_mul_f32 v[24:25], v[18:19], v[86:87] op_sel_hi:[0,1]
	v_pk_fma_f32 v[64:65], v[40:41], v[20:21], v[6:7]
	v_pk_mul_f32 v[20:21], v[18:19], v[80:81] op_sel_hi:[0,1]
	v_pk_fma_f32 v[62:63], v[38:39], v[24:25], v[8:9]
	v_pk_mul_f32 v[24:25], v[18:19], v[82:83] op_sel_hi:[0,1]
	v_pk_fma_f32 v[66:67], v[44:45], v[20:21], v[2:3]
	v_pk_mul_f32 v[20:21], v[18:19], v[76:77] op_sel_hi:[0,1]
	v_pk_fma_f32 v[32:33], v[42:43], v[24:25], v[4:5]
	v_pk_mul_f32 v[24:25], v[18:19], v[78:79] op_sel_hi:[0,1]
	v_pk_fma_f32 v[30:31], v[48:49], v[20:21], v[14:15]
	v_pk_mul_f32 v[20:21], v[18:19], v[88:89] op_sel_hi:[0,1]
	v_pk_mul_f32 v[18:19], v[18:19], v[90:91] op_sel_hi:[0,1]
	v_pk_fma_f32 v[28:29], v[46:47], v[24:25], v[16:17]
	v_pk_fma_f32 v[58:59], v[50:51], v[18:19], v[12:13]
	v_pk_fma_f32 v[60:61], v[52:53], v[20:21], v[10:11]
	v_lshl_add_u64 v[24:25], v[56:57], 0, s[20:21]
	v_cvt_pk_bf16_f32 v18, v64, v65
	v_cvt_pk_bf16_f32 v19, v62, v63
	v_cvt_pk_bf16_f32 v20, v66, v67
	v_cvt_pk_bf16_f32 v21, v32, v33
	global_store_dwordx4 v[24:25], v[18:21], off
	s_mov_b32 s20, 0x3e9b6dac
	s_nop 0
	v_cvt_pk_bf16_f32 v18, v30, v31
	v_cvt_pk_bf16_f32 v19, v28, v29
	v_cvt_pk_bf16_f32 v20, v60, v61
	v_cvt_pk_bf16_f32 v21, v58, v59
	ds_read_b128 v[74:77], v72
	ds_read_b128 v[78:81], v72 offset:16
	s_waitcnt lgkmcnt(1)
	v_mul_f32_e32 v26, v65, v75
	v_mul_f32_e32 v27, v63, v77
	v_fmac_f32_e32 v26, v64, v74
	v_fmac_f32_e32 v27, v62, v76
	ds_read_b128 v[74:77], v72 offset:2048
	v_add_f32_e32 v26, v26, v27
	s_waitcnt lgkmcnt(1)
	v_mul_f32_e32 v27, v67, v79
	v_mul_f32_e32 v56, v33, v81
	v_fmac_f32_e32 v27, v66, v78
	v_fmac_f32_e32 v56, v32, v80
	ds_read_b128 v[78:81], v72 offset:2064
	v_add_f32_e32 v26, 0, v26
	v_add_f32_e32 v27, v27, v56
	v_add_f32_e32 v26, v26, v27
	s_waitcnt lgkmcnt(1)
	v_mul_f32_e32 v27, v31, v75
	v_mul_f32_e32 v56, v29, v77
	v_fmac_f32_e32 v27, v30, v74
	v_fmac_f32_e32 v56, v28, v76
	v_add_f32_e32 v27, v27, v56
	v_add_f32_e32 v26, v26, v27
	s_waitcnt lgkmcnt(0)
	v_mul_f32_e32 v27, v61, v79
	v_mul_f32_e32 v56, v59, v81
	v_fmac_f32_e32 v27, v60, v78
	v_fmac_f32_e32 v56, v58, v80
	v_add_f32_e32 v27, v27, v56
	v_add_f32_e32 v56, v26, v27
	ds_bpermute_b32 v57, v165, v56
	v_frexp_mant_f32_e32 v74, v92
	v_cmp_gt_f32_e32 vcc, s37, v74
	ds_read_b128 v[74:77], v72 offset:4096
	v_cvt_f64_f32_e32 v[26:27], v92
	s_waitcnt lgkmcnt(1)
	v_add_f32_e32 v57, v56, v57
	ds_bpermute_b32 v78, v169, v57
	v_frexp_exp_i32_f64_e32 v26, v[26:27]
	v_subbrev_co_u32_e32 v56, vcc, 0, v26, vcc
	v_sub_u32_e32 v27, 0, v56
	s_waitcnt lgkmcnt(0)
	v_add_f32_e32 v57, v57, v78
	ds_read_b128 v[78:81], v72 offset:4112
	v_mul_f32_e32 v26, v65, v75
	v_fmac_f32_e32 v26, v64, v74
	v_mul_f32_e32 v74, v63, v77
	v_fmac_f32_e32 v74, v62, v76
	v_add_f32_e32 v26, v26, v74
	s_waitcnt lgkmcnt(0)
	v_mul_f32_e32 v79, v67, v79
	ds_read_b128 v[74:77], v72 offset:6144
	v_fmac_f32_e32 v79, v66, v78
	v_mul_f32_e32 v78, v33, v81
	v_fmac_f32_e32 v78, v32, v80
	v_add_f32_e32 v26, 0, v26
	v_add_f32_e32 v78, v79, v78
	v_add_f32_e32 v26, v26, v78
	ds_read_b128 v[78:81], v72 offset:6160
	s_waitcnt lgkmcnt(1)
	v_mul_f32_e32 v75, v31, v75
	v_fmac_f32_e32 v75, v30, v74
	v_mul_f32_e32 v74, v29, v77
	v_fmac_f32_e32 v74, v28, v76
	v_add_f32_e32 v74, v75, v74
	v_add_f32_e32 v26, v26, v74
	s_waitcnt lgkmcnt(0)
	v_mul_f32_e32 v74, v61, v79
	v_mul_f32_e32 v75, v59, v81
	v_fmac_f32_e32 v74, v60, v78
	v_fmac_f32_e32 v75, v58, v80
	v_add_f32_e32 v74, v74, v75
	v_add_f32_e32 v78, v26, v74
	ds_bpermute_b32 v79, v165, v78
	ds_read_b128 v[74:77], v72 offset:8192
	ds_bpermute_b32 v82, v168, v57
	v_ldexp_f32 v26, v92, v27
	s_waitcnt lgkmcnt(2)
	v_add_f32_e32 v83, v78, v79
	ds_read_b128 v[78:81], v72 offset:8208
	s_waitcnt lgkmcnt(2)
	v_mul_f32_e32 v75, v65, v75
	v_fmac_f32_e32 v75, v64, v74
	v_mul_f32_e32 v74, v63, v77
	v_fmac_f32_e32 v74, v62, v76
	v_add_f32_e32 v74, v75, v74
	s_waitcnt lgkmcnt(0)
	v_mul_f32_e32 v79, v67, v79
	v_add_f32_e32 v85, 0, v74
	v_fmac_f32_e32 v79, v66, v78
	v_mul_f32_e32 v78, v33, v81
	ds_read_b128 v[74:77], v72 offset:10240
	v_fmac_f32_e32 v78, v32, v80
	v_add_f32_e32 v78, v79, v78
	v_add_f32_e32 v85, v85, v78
	ds_read_b128 v[78:81], v72 offset:10256
	s_waitcnt lgkmcnt(1)
	v_mul_f32_e32 v75, v31, v75
	v_fmac_f32_e32 v75, v30, v74
	v_mul_f32_e32 v74, v29, v77
	v_fmac_f32_e32 v74, v28, v76
	v_add_f32_e32 v57, v57, v82
	v_add_f32_e32 v74, v75, v74
	s_waitcnt lgkmcnt(0)
; #define LAS __attribute__((address_space(3)))
; template <int LO, int HI> __global__ void __launch_bounds__(NWAVES * 64, 2) fox_fwd(Args args) {
;     ...
;             for (int q = 0; q < 8; ++q) { float a = 0.f;
; #pragma unroll
;                 for (int j = 0; j < 4; ++j) { const f32x4 w = *(const LAS f32x4*)(wf + q * 1024 + P1COL(j)); a += (v[j][0] * w[0] + v[j][1] * w[1]) + (v[j][2] * w[2] + v[j][3] * w[3]); }
;                 fl[q] = wave_sum(a); }
	v_mul_f32_e32 v75, v61, v79
	v_mul_f32_e32 v76, v59, v81
	ds_bpermute_b32 v82, v167, v57
	v_fmac_f32_e32 v75, v60, v78
	v_fmac_f32_e32 v76, v58, v80
	v_add_f32_e32 v74, v85, v74
	v_add_f32_e32 v75, v75, v76
	v_add_f32_e32 v74, v74, v75
	ds_bpermute_b32 v84, v169, v83
	ds_bpermute_b32 v75, v165, v74
	s_waitcnt lgkmcnt(2)
	v_add_f32_e32 v57, v57, v82
	ds_bpermute_b32 v76, v166, v57
	s_waitcnt lgkmcnt(2)
	v_add_f32_e32 v77, v83, v84
	s_waitcnt lgkmcnt(1)
	v_add_f32_e32 v74, v74, v75
	ds_bpermute_b32 v78, v168, v77
	ds_bpermute_b32 v75, v169, v74
	s_waitcnt lgkmcnt(2)
	v_add_f32_e32 v57, v57, v76
	ds_bpermute_b32 v76, v164, v57
	s_waitcnt lgkmcnt(2)
	v_add_f32_e32 v78, v77, v78
	s_waitcnt lgkmcnt(1)
	v_add_f32_e32 v80, v74, v75
	ds_bpermute_b32 v79, v167, v78
	ds_bpermute_b32 v81, v168, v80
	s_waitcnt lgkmcnt(2)
	v_add_f32_e32 v57, v57, v76
	ds_read_b128 v[74:77], v72 offset:12288
	s_waitcnt lgkmcnt(2)
	v_add_f32_e32 v82, v78, v79
	s_waitcnt lgkmcnt(1)
	v_add_f32_e32 v84, v80, v81
	ds_read_b128 v[78:81], v72 offset:12304
	s_waitcnt lgkmcnt(1)
	v_mul_f32_e32 v75, v65, v75
	v_fmac_f32_e32 v75, v64, v74
	v_mul_f32_e32 v74, v63, v77
	v_fmac_f32_e32 v74, v62, v76
	v_add_f32_e32 v74, v75, v74
	s_waitcnt lgkmcnt(0)
	v_mul_f32_e32 v79, v67, v79
	v_add_f32_e32 v85, 0, v74
	v_fmac_f32_e32 v79, v66, v78
	v_mul_f32_e32 v78, v33, v81
	ds_read_b128 v[74:77], v72 offset:14336
	v_fmac_f32_e32 v78, v32, v80
	v_add_f32_e32 v78, v79, v78
	v_add_f32_e32 v85, v85, v78
	ds_read_b128 v[78:81], v72 offset:14352
	s_waitcnt lgkmcnt(1)
	v_mul_f32_e32 v75, v31, v75
	v_fmac_f32_e32 v75, v30, v74
	v_mul_f32_e32 v74, v29, v77
	v_fmac_f32_e32 v74, v28, v76
	v_add_f32_e32 v74, v75, v74
	s_waitcnt lgkmcnt(0)
	v_mul_f32_e32 v79, v61, v79
	v_add_f32_e32 v85, v85, v74
	v_fmac_f32_e32 v79, v60, v78
	v_mul_f32_e32 v78, v59, v81
	ds_read_b128 v[74:77], v72 offset:16384
	v_fmac_f32_e32 v78, v58, v80
	v_add_f32_e32 v78, v79, v78
	v_add_f32_e32 v85, v85, v78
	ds_read_b128 v[78:81], v72 offset:16400
	s_waitcnt lgkmcnt(1)
	v_mul_f32_e32 v75, v65, v75
	v_fmac_f32_e32 v75, v64, v74
	v_mul_f32_e32 v74, v63, v77
	v_fmac_f32_e32 v74, v62, v76
	v_add_f32_e32 v74, v75, v74
	s_waitcnt lgkmcnt(0)
	v_mul_f32_e32 v79, v67, v79
	v_add_f32_e32 v87, 0, v74
	v_fmac_f32_e32 v79, v66, v78
	v_mul_f32_e32 v78, v33, v81
	ds_read_b128 v[74:77], v72 offset:18432
	v_fmac_f32_e32 v78, v32, v80
	v_add_f32_e32 v78, v79, v78
	v_add_f32_e32 v87, v87, v78
	ds_read_b128 v[78:81], v72 offset:18448
	s_waitcnt lgkmcnt(1)
	v_mul_f32_e32 v75, v31, v75
	v_fmac_f32_e32 v75, v30, v74
	v_mul_f32_e32 v74, v29, v77
	v_fmac_f32_e32 v74, v28, v76
	v_add_f32_e32 v74, v75, v74
	s_waitcnt lgkmcnt(0)
	v_mul_f32_e32 v75, v61, v79
	v_mul_f32_e32 v76, v59, v81
	v_fmac_f32_e32 v75, v60, v78
	v_fmac_f32_e32 v76, v58, v80
	v_add_f32_e32 v74, v87, v74
	v_add_f32_e32 v75, v75, v76
	v_add_f32_e32 v74, v74, v75
	ds_bpermute_b32 v86, v165, v85
	ds_bpermute_b32 v75, v165, v74
	ds_bpermute_b32 v76, v167, v84
	ds_bpermute_b32 v83, v166, v82
	s_waitcnt lgkmcnt(3)
	v_add_f32_e32 v77, v85, v86
	s_waitcnt lgkmcnt(2)
	v_add_f32_e32 v74, v74, v75
	ds_bpermute_b32 v78, v169, v77
	ds_bpermute_b32 v75, v169, v74
	s_waitcnt lgkmcnt(3)
	v_add_f32_e32 v76, v84, v76
	ds_bpermute_b32 v80, v166, v76
	s_waitcnt lgkmcnt(3)
	v_add_f32_e32 v79, v82, v83
	s_waitcnt lgkmcnt(2)
	v_add_f32_e32 v77, v77, v78
	s_waitcnt lgkmcnt(1)
	v_add_f32_e32 v74, v74, v75
	ds_bpermute_b32 v78, v168, v77
	ds_bpermute_b32 v75, v168, v74
	ds_bpermute_b32 v81, v164, v79
	s_waitcnt lgkmcnt(3)
	v_add_f32_e32 v76, v76, v80
	ds_bpermute_b32 v82, v164, v76
	s_waitcnt lgkmcnt(3)
	v_add_f32_e32 v77, v77, v78
	s_waitcnt lgkmcnt(2)
	v_add_f32_e32 v75, v74, v75
	ds_bpermute_b32 v78, v167, v77
	ds_bpermute_b32 v80, v167, v75
	s_waitcnt lgkmcnt(3)
	v_add_f32_e32 v74, v79, v81
	s_waitcnt lgkmcnt(1)
	v_add_f32_e32 v77, v77, v78
	s_waitcnt lgkmcnt(0)
	v_add_f32_e32 v79, v75, v80
	ds_bpermute_b32 v78, v166, v77
	ds_bpermute_b32 v84, v166, v79
	v_add_f32_e32 v75, v76, v82
	ds_read_b128 v[80:83], v72 offset:20480
	s_waitcnt lgkmcnt(2)
	v_add_f32_e32 v76, v77, v78
	s_waitcnt lgkmcnt(1)
	v_add_f32_e32 v78, v79, v84
	ds_read_b128 v[84:87], v72 offset:20496
	s_waitcnt lgkmcnt(1)
	v_mul_f32_e32 v81, v65, v81
	v_fmac_f32_e32 v81, v64, v80
	v_mul_f32_e32 v80, v63, v83
	v_fmac_f32_e32 v80, v62, v82
	v_add_f32_e32 v80, v81, v80
	s_waitcnt lgkmcnt(0)
	v_mul_f32_e32 v85, v67, v85
	v_add_f32_e32 v88, 0, v80
	v_fmac_f32_e32 v85, v66, v84
	v_mul_f32_e32 v84, v33, v87
	ds_read_b128 v[80:83], v72 offset:22528
	v_fmac_f32_e32 v84, v32, v86
	v_add_f32_e32 v84, v85, v84
	v_add_f32_e32 v88, v88, v84
	ds_read_b128 v[84:87], v72 offset:22544
	s_waitcnt lgkmcnt(1)
	v_mul_f32_e32 v81, v31, v81
	v_fmac_f32_e32 v81, v30, v80
	v_mul_f32_e32 v80, v29, v83
	v_fmac_f32_e32 v80, v28, v82
	v_add_f32_e32 v80, v81, v80
	s_waitcnt lgkmcnt(0)
	v_mul_f32_e32 v81, v61, v85
	v_fmac_f32_e32 v81, v60, v84
	ds_read_b128 v[82:85], v72 offset:24576
	v_mul_f32_e32 v87, v59, v87
	v_fmac_f32_e32 v87, v58, v86
	v_add_f32_e32 v80, v88, v80
	v_add_f32_e32 v81, v81, v87
	ds_read_b128 v[86:89], v72 offset:24592
	s_waitcnt lgkmcnt(1)
	v_pk_mul_f32 v[82:83], v[64:65], v[82:83]
	v_pk_mul_f32 v[84:85], v[62:63], v[84:85]
	v_add_f32_e32 v80, v80, v81
	v_pk_mov_b32 v[90:91], v[82:83], v[84:85] op_sel:[1,0]
	v_mov_b32_e32 v83, v85
	v_pk_add_f32 v[82:83], v[90:91], v[82:83]
	s_waitcnt lgkmcnt(0)
	v_pk_mul_f32 v[86:87], v[66:67], v[86:87]
	v_add_f32_e32 v82, v82, v83
	v_add_f32_e32 v94, 0, v82
	ds_read_b128 v[82:85], v72 offset:26624
	ds_read_b128 v[90:93], v72 offset:26640
	v_pk_mul_f32 v[88:89], v[32:33], v[88:89]
	ds_bpermute_b32 v81, v165, v80
	v_pk_mov_b32 v[96:97], v[86:87], v[88:89] op_sel:[1,0]
	v_mov_b32_e32 v87, v89
	v_pk_add_f32 v[86:87], v[96:97], v[86:87]
	s_waitcnt lgkmcnt(1)
; #define LAS __attribute__((address_space(3)))
; template <int LO, int HI> __global__ void __launch_bounds__(NWAVES * 64, 2) fox_fwd(Args args) {
;     ...
;             for (int q = 0; q < 8; ++q) { float a = 0.f;
; #pragma unroll
;                 for (int j = 0; j < 4; ++j) { const f32x4 w = *(const LAS f32x4*)(wf + q * 1024 + P1COL(j)); a += (v[j][0] * w[0] + v[j][1] * w[1]) + (v[j][2] * w[2] + v[j][3] * w[3]); }
;                 fl[q] = wave_sum(a); }
;             float mine = fl[0];
; #pragma unroll
;             for (int q = 1; q < 8; ++q) mine = (lane == q) ? fl[q] : mine;
;             { const float z = mine + bfv; const float ls = fminf(z, 0.f) - log1pf(__expf(-fabsf(z)));
	v_mul_f32_e32 v88, v61, v91
	v_pk_add_f32 v[86:87], v[86:87], v[86:87] op_sel:[0,1] op_sel_hi:[1,0]
	v_mul_f32_e32 v95, v60, v90
	v_mov_b32_e32 v87, v88
	v_pk_add_f32 v[88:89], v[94:95], v[86:87]
	v_mul_f32_e32 v86, v31, v83
	v_pk_fma_f32 v[82:83], v[30:31], v[82:83], v[86:87] op_sel_hi:[1,1,0]
	v_mul_f32_e32 v86, v29, v85
	v_mul_f32_e32 v90, v58, v92
	v_mul_f32_e32 v91, v59, v93
	v_pk_fma_f32 v[84:85], v[28:29], v[84:85], v[86:87] op_sel_hi:[1,1,0]
	v_mov_b32_e32 v83, v90
	v_mov_b32_e32 v85, v91
	v_pk_add_f32 v[82:83], v[82:83], v[84:85]
	ds_read_b128 v[84:87], v72 offset:28672
	v_pk_add_f32 v[82:83], v[88:89], v[82:83]
	ds_read_b128 v[88:91], v72 offset:28688
	v_add_f32_e32 v82, v82, v83
	ds_bpermute_b32 v83, v165, v82
	s_waitcnt lgkmcnt(2)
	v_pk_mul_f32 v[64:65], v[64:65], v[84:85]
	v_pk_mul_f32 v[62:63], v[62:63], v[86:87]
	s_waitcnt lgkmcnt(1)
	v_pk_mul_f32 v[66:67], v[66:67], v[88:89]
	v_pk_mov_b32 v[84:85], v[64:65], v[62:63] op_sel:[1,0]
	v_mov_b32_e32 v65, v63
	v_pk_add_f32 v[62:63], v[84:85], v[64:65]
	v_pk_mul_f32 v[32:33], v[32:33], v[90:91]
	v_add_f32_e32 v62, v62, v63
	v_add_f32_e32 v92, 0, v62
	ds_read_b128 v[62:65], v72 offset:30720
	ds_read_b128 v[84:87], v72 offset:30736
	v_pk_mov_b32 v[88:89], v[66:67], v[32:33] op_sel:[1,0]
	v_mov_b32_e32 v67, v33
	v_pk_add_f32 v[32:33], v[88:89], v[66:67]
	ds_bpermute_b32 v77, v164, v76
	s_waitcnt lgkmcnt(1)
	v_mul_f32_e32 v93, v60, v84
	v_mul_f32_e32 v60, v61, v85
	v_mul_f32_e32 v61, v58, v86
	v_mul_f32_e32 v59, v59, v87
	v_mul_f32_e32 v58, v31, v63
	v_pk_fma_f32 v[30:31], v[30:31], v[62:63], v[58:59] op_sel_hi:[1,1,0]
	v_mul_f32_e32 v58, v29, v65
	v_pk_add_f32 v[32:33], v[32:33], v[32:33] op_sel:[0,1] op_sel_hi:[1,0]
	v_pk_fma_f32 v[28:29], v[28:29], v[64:65], v[58:59] op_sel_hi:[1,1,0]
	v_mov_b32_e32 v33, v60
	v_mov_b32_e32 v31, v61
	v_mov_b32_e32 v29, v59
	v_pk_add_f32 v[32:33], v[92:93], v[32:33]
	v_pk_add_f32 v[28:29], v[30:31], v[28:29]
	v_add_f32_e32 v30, v80, v81
	v_pk_add_f32 v[28:29], v[32:33], v[28:29]
	ds_bpermute_b32 v31, v169, v30
	v_add_f32_e32 v28, v28, v29
	ds_bpermute_b32 v29, v165, v28
	v_add_f32_e32 v32, v82, v83
	ds_bpermute_b32 v33, v169, v32
	s_waitcnt lgkmcnt(2)
	v_add_f32_e32 v30, v30, v31
	ds_bpermute_b32 v31, v168, v30
	s_waitcnt lgkmcnt(2)
	v_add_f32_e32 v28, v28, v29
	ds_bpermute_b32 v29, v169, v28
	s_waitcnt lgkmcnt(2)
	v_add_f32_e32 v32, v32, v33
	ds_bpermute_b32 v33, v168, v32
	s_waitcnt lgkmcnt(2)
	v_add_f32_e32 v30, v30, v31
	ds_bpermute_b32 v31, v167, v30
	s_waitcnt lgkmcnt(2)
	v_add_f32_e32 v28, v28, v29
	ds_bpermute_b32 v29, v168, v28
	s_waitcnt lgkmcnt(2)
	v_add_f32_e32 v32, v32, v33
	ds_bpermute_b32 v33, v167, v32
	s_waitcnt lgkmcnt(2)
	v_add_f32_e32 v30, v30, v31
	ds_bpermute_b32 v31, v166, v30
	s_waitcnt lgkmcnt(2)
	v_add_f32_e32 v28, v28, v29
	ds_bpermute_b32 v29, v167, v28
	s_waitcnt lgkmcnt(2)
	v_add_f32_e32 v32, v32, v33
	ds_bpermute_b32 v33, v166, v32
	ds_bpermute_b32 v79, v164, v78
	s_waitcnt lgkmcnt(3)
	v_add_f32_e32 v30, v30, v31
	s_waitcnt lgkmcnt(2)
	v_add_f32_e32 v28, v28, v29
	ds_bpermute_b32 v29, v166, v28
	ds_bpermute_b32 v31, v164, v30
	s_waitcnt lgkmcnt(3)
	v_add_f32_e32 v32, v32, v33
	ds_bpermute_b32 v33, v164, v32
	v_add_f32_e32 v58, v76, v77
	s_waitcnt lgkmcnt(2)
	v_add_f32_e32 v28, v28, v29
	ds_bpermute_b32 v29, v164, v28
	v_add_f32_e32 v59, v78, v79
	s_waitcnt lgkmcnt(2)
	v_add_f32_e32 v30, v30, v31
	s_waitcnt lgkmcnt(1)
	v_add_f32_e32 v31, v32, v33
	global_store_dwordx4 v[24:25], v[18:21], off offset:1024
	s_waitcnt lgkmcnt(0)
	v_add_f32_e32 v28, v28, v29
	v_cndmask_b32_e64 v29, v57, v74, s[4:5]
	v_cndmask_b32_e64 v29, v29, v75, s[6:7]
	v_cndmask_b32_e64 v29, v29, v58, s[8:9]
	v_cndmask_b32_e64 v29, v29, v59, s[10:11]
	v_cndmask_b32_e64 v29, v29, v30, s[12:13]
	v_cndmask_b32_e64 v29, v29, v31, s[14:15]
	v_cndmask_b32_e64 v28, v29, v28, s[16:17]
	v_add_f32_e32 v29, v71, v28
	v_mul_f32_e64 v28, |v29|, s29
	v_exp_f32_e32 v78, v28
	v_ldexp_f32 v28, v23, v27
	v_min_f32_e32 v23, 0, v29
	v_add_f32_e32 v20, 1.0, v78
	v_add_f32_e32 v18, -1.0, v20
	v_sub_f32_e32 v19, v18, v20
	v_add_f32_e32 v19, 1.0, v19
	v_sub_f32_e32 v18, v78, v18
	v_add_f32_e32 v21, v18, v19
	v_frexp_mant_f32_e32 v24, v20
	v_cvt_f64_f32_e32 v[18:19], v20
	v_frexp_exp_i32_f64_e32 v18, v[18:19]
	v_cmp_gt_f32_e32 vcc, s37, v24
	s_nop 1
	v_subbrev_co_u32_e32 v57, vcc, 0, v18, vcc
	v_sub_u32_e32 v18, 0, v57
	v_ldexp_f32 v27, v20, v18
	v_ldexp_f32 v29, v21, v18
	v_pk_add_f32 v[18:19], v[26:27], 1.0 op_sel_hi:[1,0]
	v_pk_add_f32 v[32:33], v[26:27], -1.0 op_sel_hi:[1,0]
	v_pk_add_f32 v[20:21], v[18:19], -1.0 op_sel_hi:[1,0]
	v_pk_add_f32 v[58:59], v[32:33], 1.0 op_sel_hi:[1,0]
	v_pk_add_f32 v[20:21], v[26:27], v[20:21] neg_lo:[0,1] neg_hi:[0,1]
	v_pk_add_f32 v[26:27], v[26:27], v[58:59] neg_lo:[0,1] neg_hi:[0,1]
	v_pk_add_f32 v[20:21], v[28:29], v[20:21]
	v_pk_add_f32 v[26:27], v[28:29], v[26:27]
	v_pk_add_f32 v[24:25], v[18:19], v[20:21]
	v_pk_add_f32 v[28:29], v[32:33], v[26:27]
	v_rcp_f32_e32 v30, v24
	v_rcp_f32_e32 v31, v25
	v_pk_add_f32 v[18:19], v[24:25], v[18:19] neg_lo:[0,1] neg_hi:[0,1]
	v_pk_add_f32 v[32:33], v[28:29], v[32:33] neg_lo:[0,1] neg_hi:[0,1]
	v_pk_add_f32 v[18:19], v[20:21], v[18:19] neg_lo:[0,1] neg_hi:[0,1]
	v_pk_mul_f32 v[20:21], v[28:29], v[30:31]
	v_pk_add_f32 v[26:27], v[26:27], v[32:33] neg_lo:[0,1] neg_hi:[0,1]
	v_pk_mul_f32 v[32:33], v[24:25], v[20:21]
	v_cmp_neq_f32_e32 vcc, s46, v55
	v_pk_fma_f32 v[58:59], v[20:21], v[24:25], v[32:33] neg_lo:[0,0,1] neg_hi:[0,0,1]
	s_nop 0
	v_pk_fma_f32 v[58:59], v[20:21], v[18:19], v[58:59]
	s_nop 0
	v_pk_add_f32 v[60:61], v[32:33], v[58:59]
	s_nop 0
	v_pk_add_f32 v[62:63], v[28:29], v[60:61] neg_lo:[0,1] neg_hi:[0,1]
; template <int LO, int HI> __global__ void __launch_bounds__(NWAVES * 64, 2) fox_fwd(Args args) {
;     ...
;             { const float z = mine + bfv; const float ls = fminf(z, 0.f) - log1pf(__expf(-fabsf(z)));
; #pragma unroll
;               for (int k = 0; k < 4; ++k)
; #pragma unroll
;                   for (int e = 0; e < 4; ++e) lsq[k][e] = (r == 4 * k + e) ? ls : lsq[k][e]; }
	v_pk_add_f32 v[32:33], v[60:61], v[32:33] neg_lo:[0,1] neg_hi:[0,1]
	v_pk_add_f32 v[28:29], v[28:29], v[62:63] neg_lo:[0,1] neg_hi:[0,1]
	s_nop 0
	v_pk_add_f32 v[28:29], v[28:29], v[60:61] neg_lo:[0,1] neg_hi:[0,1]
	s_nop 0
	v_pk_add_f32 v[26:27], v[26:27], v[28:29]
	v_pk_add_f32 v[28:29], v[32:33], v[58:59] neg_lo:[0,1] neg_hi:[0,1]
	s_nop 0
	v_pk_add_f32 v[26:27], v[28:29], v[26:27]
	s_nop 0
	v_pk_add_f32 v[28:29], v[62:63], v[26:27]
	s_nop 0
	v_pk_mul_f32 v[32:33], v[30:31], v[28:29]
	s_nop 0
	v_pk_mul_f32 v[58:59], v[24:25], v[32:33]
	s_nop 0
	v_pk_fma_f32 v[24:25], v[32:33], v[24:25], v[58:59] neg_lo:[0,0,1] neg_hi:[0,0,1]
	s_nop 0
	v_pk_fma_f32 v[18:19], v[32:33], v[18:19], v[24:25]
	v_pk_add_f32 v[24:25], v[62:63], v[28:29] neg_lo:[0,1] neg_hi:[0,1]
	s_nop 0
	v_pk_add_f32 v[24:25], v[26:27], v[24:25]
	v_pk_add_f32 v[26:27], v[58:59], v[18:19]
	s_nop 0
	v_pk_add_f32 v[60:61], v[28:29], v[26:27] neg_lo:[0,1] neg_hi:[0,1]
	v_pk_add_f32 v[58:59], v[26:27], v[58:59] neg_lo:[0,1] neg_hi:[0,1]
	v_pk_add_f32 v[28:29], v[28:29], v[60:61] neg_lo:[0,1] neg_hi:[0,1]
	v_pk_add_f32 v[18:19], v[58:59], v[18:19] neg_lo:[0,1] neg_hi:[0,1]
	v_pk_add_f32 v[26:27], v[28:29], v[26:27] neg_lo:[0,1] neg_hi:[0,1]
	s_nop 0
	v_pk_add_f32 v[24:25], v[24:25], v[26:27]
	s_nop 0
	v_pk_add_f32 v[18:19], v[18:19], v[24:25]
	v_pk_add_f32 v[24:25], v[20:21], v[32:33]
	v_pk_add_f32 v[18:19], v[60:61], v[18:19]
	v_pk_add_f32 v[20:21], v[24:25], v[20:21] neg_lo:[0,1] neg_hi:[0,1]
	v_pk_mul_f32 v[18:19], v[30:31], v[18:19]
	v_pk_add_f32 v[20:21], v[32:33], v[20:21] neg_lo:[0,1] neg_hi:[0,1]
	v_cvt_f32_i32_e32 v32, v56
	v_pk_add_f32 v[18:19], v[20:21], v[18:19]
	v_cvt_f32_i32_e32 v33, v57
	v_pk_add_f32 v[26:27], v[24:25], v[18:19]
	s_nop 0
	v_pk_add_f32 v[20:21], v[26:27], v[24:25] neg_lo:[0,1] neg_hi:[0,1]
	v_pk_mul_f32 v[28:29], v[26:27], v[26:27]
	v_pk_add_f32 v[18:19], v[18:19], v[20:21] neg_lo:[0,1] neg_hi:[0,1]
	v_mov_b32_e32 v20, 0x3ecc95a3
	v_pk_fma_f32 v[30:31], v[28:29], s[20:21], v[20:21] op_sel_hi:[1,0,0]
	s_mov_b32 s20, 0x3f2aaada
	v_ldexp_f32 v24, v26, 1
	v_pk_fma_f32 v[30:31], v[28:29], v[30:31], s[20:21] op_sel_hi:[1,1,0]
	v_ldexp_f32 v25, v27, 1
	v_pk_mul_f32 v[26:27], v[26:27], v[28:29]
	v_pk_mul_f32 v[28:29], v[32:33], s[36:37] op_sel_hi:[1,0]
	v_pk_mul_f32 v[26:27], v[26:27], v[30:31]
	v_pk_fma_f32 v[58:59], v[32:33], s[36:37], v[28:29] op_sel_hi:[1,0,1] neg_lo:[0,0,1] neg_hi:[0,0,1]
	v_pk_add_f32 v[30:31], v[24:25], v[26:27]
	s_mov_b32 s20, 0xb102e308
	v_pk_add_f32 v[24:25], v[30:31], v[24:25] neg_lo:[0,1] neg_hi:[0,1]
	v_ldexp_f32 v57, v19, 1
	v_pk_fma_f32 v[32:33], v[32:33], s[20:21], v[58:59] op_sel_hi:[1,0,1]
	v_pk_add_f32 v[24:25], v[26:27], v[24:25] neg_lo:[0,1] neg_hi:[0,1]
	v_ldexp_f32 v18, v18, 1
	v_mov_b32_e32 v26, v28
	v_mov_b32_e32 v27, v25
	v_mov_b32_e32 v56, v32
	v_mov_b32_e32 v19, v57
	v_pk_add_f32 v[26:27], v[26:27], v[56:57]
	v_pk_add_f32 v[56:57], v[18:19], v[24:25]
	v_mov_b32_e32 v25, v31
	v_mov_b32_e32 v19, v57
	v_pk_add_f32 v[58:59], v[28:29], v[32:33]
	v_pk_add_f32 v[18:19], v[18:19], v[24:25]
	v_pk_add_f32 v[24:25], v[30:31], v[56:57]
	v_mov_b32_e32 v74, v30
	v_pk_add_f32 v[60:61], v[58:59], v[24:25]
	v_mov_b32_e32 v66, v24
	v_mov_b32_e32 v67, v61
	v_mov_b32_e32 v75, v59
	v_pk_add_f32 v[66:67], v[66:67], v[74:75] neg_lo:[0,1] neg_hi:[0,1]
	v_mov_b32_e32 v62, v60
	v_mov_b32_e32 v63, v59
	v_mov_b32_e32 v64, v58
	v_mov_b32_e32 v65, v29
	v_mov_b32_e32 v74, v58
	v_mov_b32_e32 v75, v61
	v_mov_b32_e32 v29, v67
	v_pk_add_f32 v[62:63], v[62:63], v[64:65] neg_lo:[0,1] neg_hi:[0,1]
	v_mov_b32_e32 v64, v24
	v_mov_b32_e32 v65, v33
	v_pk_add_f32 v[28:29], v[74:75], v[28:29] neg_lo:[0,1] neg_hi:[0,1]
	v_pk_add_f32 v[64:65], v[64:65], v[62:63] neg_lo:[0,1] neg_hi:[0,1]
	v_mov_b32_e32 v74, v28
	v_mov_b32_e32 v75, v63
	v_mov_b32_e32 v76, v60
	v_mov_b32_e32 v77, v25
	v_mov_b32_e32 v63, v31
	v_pk_add_f32 v[74:75], v[32:33], v[74:75] neg_lo:[0,1] neg_hi:[0,1]
	v_pk_add_f32 v[62:63], v[76:77], v[62:63] neg_lo:[0,1] neg_hi:[0,1]
	v_mov_b32_e32 v33, v59
	v_pk_add_f32 v[26:27], v[26:27], v[62:63] neg_lo:[0,1] neg_hi:[0,1]
	v_pk_add_f32 v[28:29], v[32:33], v[28:29] neg_lo:[0,1] neg_hi:[0,1]
	v_pk_add_f32 v[18:19], v[18:19], v[66:67] neg_lo:[0,1] neg_hi:[0,1]
	v_pk_add_f32 v[24:25], v[24:25], v[30:31] neg_lo:[0,1] neg_hi:[0,1]
	v_pk_add_f32 v[30:31], v[18:19], v[28:29]
	v_mov_b32_e32 v29, v65
	v_mov_b32_e32 v19, v27
	v_pk_add_f32 v[32:33], v[64:65], v[26:27]
	v_pk_add_f32 v[18:19], v[28:29], v[18:19]
	v_mov_b32_e32 v26, v30
	v_pk_add_f32 v[18:19], v[18:19], v[74:75] neg_lo:[0,1] neg_hi:[0,1]
	v_mov_b32_e32 v27, v33
	v_pk_add_f32 v[24:25], v[56:57], v[24:25] neg_lo:[0,1] neg_hi:[0,1]
	v_pk_add_f32 v[26:27], v[26:27], v[18:19] neg_lo:[0,1] neg_hi:[0,1]
	v_pk_add_f32 v[18:19], v[24:25], v[18:19] neg_lo:[0,1] neg_hi:[0,1]
	v_pk_add_f32 v[26:27], v[28:29], v[26:27] neg_lo:[0,1] neg_hi:[0,1]
	v_pk_add_f32 v[24:25], v[32:33], v[30:31]
	v_pk_add_f32 v[18:19], v[18:19], v[26:27]
	v_pk_add_f32 v[26:27], v[60:61], v[24:25]
	v_mov_b32_e32 v64, 0x7f800000
	v_pk_add_f32 v[28:29], v[26:27], v[60:61] neg_lo:[0,1] neg_hi:[0,1]
	v_mov_b32_e32 v65, 0x7fc00000
	v_pk_add_f32 v[24:25], v[24:25], v[28:29] neg_lo:[0,1] neg_hi:[0,1]
	v_mov_b32_e32 v66, 0xff800000
	v_pk_add_f32 v[18:19], v[18:19], v[24:25]
	s_add_u32 s20, s26, s34
	v_pk_add_f32 v[18:19], v[26:27], v[18:19]
	s_addc_u32 s21, s27, s35
	v_cndmask_b32_e32 v18, v64, v18, vcc
	v_cmp_neq_f32_e32 vcc, s46, v78
	s_mov_b64 s[34:35], 0x2000
	v_mov_b32_e32 v58, 0x3f317218
	v_cndmask_b32_e32 v19, v64, v19, vcc
	v_cmp_ngt_f32_e32 vcc, -1.0, v78
	v_mov_b32_e32 v21, v37
	v_mov_b32_e32 v30, v37
	v_cndmask_b32_e32 v19, v65, v19, vcc
; #define GAS __attribute__((address_space(1)))
; #define LAS __attribute__((address_space(3)))
; template <int LO, int HI> __global__ void __launch_bounds__(NWAVES * 64, 2) fox_fwd(Args args) {
;     ...
;         for (int r = 0; r < 16; ++r) { const int m = m0 + r;
;             const GAS float* xr = (const GAS float*)(x + (size_t)m * D);
;             f32x4 v[4]; float s2 = 0.f;
; #pragma unroll
;             for (int j = 0; j < 4; ++j) { v[j] = *(const GAS f32x4*)(xr + P1COL(j)); s2 += (v[j][0] * v[j][0] + v[j][1] * v[j][1]) + (v[j][2] * v[j][2] + v[j][3] * v[j][3]); }
;             const float rstd = 1.0f / sqrtf(wave_sum(s2) * (1.0f / D) + EPS);
; #pragma unroll
;             for (int j = 0; j < 4; ++j) v[j] = v[j] * rstd * gm[j] + sh[j];
;     ...
;                 for (int j = 0; j < 4; ++j) { const f32x4 w = *(const LAS f32x4*)(wf + q * 1024 + P1COL(j)); a += (v[j][0] * w[0] + v[j][1] * w[1]) + (v[j][2] * w[2] + v[j][3] * w[3]); }
	v_cmp_ngt_f32_e32 vcc, -1.0, v55
	v_mov_b32_e32 v31, v37
	v_mov_b32_e32 v32, v37
	v_cndmask_b32_e32 v18, v65, v18, vcc
	v_cmp_neq_f32_e32 vcc, -1.0, v55
	v_mov_b32_e32 v33, v37
	v_mov_b32_e32 v26, v37
	v_cndmask_b32_e32 v18, v66, v18, vcc
	v_cmp_neq_f32_e32 vcc, -1.0, v78
	v_mov_b32_e32 v27, v37
	v_mov_b32_e32 v28, v37
	v_cndmask_b32_e32 v19, v66, v19, vcc
	v_cmp_lt_f32_e64 vcc, |v78|, s47
	v_mov_b32_e32 v29, v37
	v_mov_b32_e32 v24, v37
	v_cndmask_b32_e32 v19, v19, v78, vcc
	v_cmp_lt_f32_e64 vcc, |v55|, s47
	v_mov_b32_e32 v25, v37
	s_nop 0
	v_cndmask_b32_e32 v18, v18, v55, vcc
	v_pk_add_f32 v[18:19], v[22:23], v[18:19] neg_lo:[0,1] neg_hi:[0,1]
	v_mov_b32_e32 v55, v37
	v_lshl_add_u64 v[22:23], s[20:21], 0, v[36:37]
	s_mov_b64 s[20:21], 0x2001400
	v_lshl_add_u64 v[54:55], s[30:31], 0, v[54:55]
	v_lshl_add_u64 v[56:57], v[22:23], 0, s[20:21]
	s_mov_b64 s[30:31], 0
	v_mov_b32_e32 v22, v37
	v_mov_b32_e32 v23, v37
	ds_read_b128 v[100:103], v72
	ds_read_b128 v[104:107], v72 offset:16
	ds_read_b128 v[108:111], v72 offset:2048
	ds_read_b128 v[112:115], v72 offset:2064
	ds_read_b128 v[116:119], v72 offset:4096
	ds_read_b128 v[120:123], v72 offset:4112
	ds_read_b128 v[124:127], v72 offset:6144
	ds_read_b128 v[128:131], v72 offset:6160
	ds_read_b128 v[132:135], v72 offset:8192
	ds_read_b128 v[136:139], v72 offset:8208
	ds_read_b128 v[140:143], v72 offset:10240
	ds_read_b128 v[144:147], v72 offset:10256
	s_waitcnt lgkmcnt(0)
	ds_read_b128 v[148:151], v72 offset:12288
	ds_read_b128 v[152:155], v72 offset:12304
	ds_read_b128 v[156:159], v72 offset:14336
	ds_read_b128 v[170:173], v72 offset:14352
	ds_read_b128 v[174:177], v72 offset:16384
	ds_read_b128 v[178:181], v72 offset:16400
	ds_read_b128 v[182:185], v72 offset:18432
	ds_read_b128 v[186:189], v72 offset:18448
	ds_read_b128 v[190:193], v72 offset:20480
	ds_read_b128 v[194:197], v72 offset:20496
	ds_read_b128 v[198:201], v72 offset:22528
	ds_read_b128 v[202:205], v72 offset:22544
	s_waitcnt lgkmcnt(0)
	ds_read_b128 v[206:209], v72 offset:24576
	ds_read_b128 v[210:213], v72 offset:24592
	ds_read_b128 v[226:229], v72 offset:26624
	ds_read_b128 v[230:233], v72 offset:26640
	ds_read_b128 v[234:237], v72 offset:28672
	ds_read_b128 v[238:241], v72 offset:28688
	ds_read_b128 v[242:245], v72 offset:30720
	ds_read_b128 v[246:249], v72 offset:30736
	s_waitcnt lgkmcnt(0)
.LBB0_131:
	v_lshl_add_u64 v[60:61], v[54:55], 0, s[30:31]
	v_add_co_u32_e32 v88, vcc, s48, v60
	v_lshl_add_u64 v[86:87], v[60:61], 0, s[34:35]
	s_nop 0
	v_addc_co_u32_e32 v89, vcc, 0, v61, vcc
	v_lshl_add_u64 v[90:91], v[60:61], 0, s[38:39]
	global_load_dwordx4 v[60:63], v[88:89], off
	global_load_dwordx4 v[74:77], v[86:87], off offset:16
	global_load_dwordx4 v[78:81], v[90:91], off offset:16
	global_load_dwordx4 v[82:85], v[88:89], off offset:2048
	s_cmp_eq_u32 s30, 0
	s_waitcnt vmcnt(3)
	v_pk_mul_f32 v[86:87], v[62:63], v[62:63]
	v_pk_mul_f32 v[88:89], v[60:61], v[60:61]
	s_waitcnt vmcnt(2)
	v_pk_mul_f32 v[90:91], v[76:77], v[76:77]
	v_pk_mul_f32 v[92:93], v[74:75], v[74:75]
	v_pk_mov_b32 v[96:97], v[88:89], v[86:87] op_sel:[1,0]
	v_mov_b32_e32 v89, v87
	v_pk_mov_b32 v[86:87], v[92:93], v[90:91] op_sel:[1,0]
	v_mov_b32_e32 v93, v91
	s_waitcnt vmcnt(0)
	v_mul_f32_e32 v36, v83, v83
	v_mul_f32_e32 v94, v85, v85
	v_pk_add_f32 v[88:89], v[96:97], v[88:89]
	v_pk_add_f32 v[86:87], v[86:87], v[92:93]
	v_mul_f32_e32 v59, v78, v78
	v_mul_f32_e32 v67, v79, v79
	v_mul_f32_e32 v98, v80, v80
	v_mul_f32_e32 v99, v81, v81
	v_pk_fma_f32 v[90:91], v[82:83], v[82:83], v[36:37] op_sel_hi:[1,1,0]
	v_pk_fma_f32 v[94:95], v[84:85], v[84:85], v[94:95] op_sel_hi:[1,1,0]
	v_pk_add_f32 v[88:89], v[88:89], v[88:89] op_sel:[0,1] op_sel_hi:[1,0]
	v_pk_add_f32 v[86:87], v[86:87], v[86:87] op_sel:[0,1] op_sel_hi:[1,0]
	v_mov_b32_e32 v91, v98
	v_mov_b32_e32 v95, v99
	v_mov_b32_e32 v89, v59
	v_mov_b32_e32 v87, v67
	v_pk_add_f32 v[90:91], v[90:91], v[94:95]
	v_pk_add_f32 v[86:87], v[88:89], v[86:87]
	s_nop 0
	v_pk_add_f32 v[86:87], v[86:87], v[90:91]
	s_nop 0
	v_add_f32_e32 v36, v86, v87
	s_waitcnt lgkmcnt(0)
	s_nop 1
	v_add_f32_dpp v59, v36, v36 quad_perm:[1,0,3,2] row_mask:0xf bank_mask:0xf
	s_nop 1
	v_add_f32_dpp v36, v59, v59 quad_perm:[2,3,0,1] row_mask:0xf bank_mask:0xf
	s_nop 1
	v_add_f32_dpp v59, v36, v36 row_half_mirror row_mask:0xf bank_mask:0xf
	s_nop 1
	v_add_f32_dpp v36, v59, v59 row_mirror row_mask:0xf bank_mask:0xf
	v_mov_b32_e32 v59, v36
	s_nop 1
	v_permlane16_swap_b32_e32 v59, v36
	v_add_f32_e32 v59, v59, v36
	v_mov_b32_e32 v36, v59
	s_nop 1
	v_permlane32_swap_b32_e32 v36, v59
	v_add_f32_e32 v36, v36, v59
	v_fmamk_f32 v36, v36, 0x3a800000, v69
	v_mul_f32_e32 v59, 0x4f800000, v36
	v_cmp_gt_f32_e32 vcc, s45, v36
	s_nop 1
	v_cndmask_b32_e32 v36, v36, v59, vcc
	v_sqrt_f32_e32 v59, v36
	s_nop 0
	v_add_u32_e32 v67, -1, v59
	v_add_u32_e32 v86, 1, v59
	v_fma_f32 v87, -v67, v59, v36
	v_fma_f32 v88, -v86, v59, v36
	v_cmp_ge_f32_e64 s[20:21], 0, v87
	s_nop 1
	v_cndmask_b32_e64 v59, v59, v67, s[20:21]
	v_cmp_lt_f32_e64 s[20:21], 0, v88
	s_nop 1
	v_cndmask_b32_e64 v59, v59, v86, s[20:21]
	v_mul_f32_e32 v67, 0x37800000, v59
	v_cndmask_b32_e32 v59, v59, v67, vcc
	v_cmp_class_f32_e32 vcc, v36, v70
	s_nop 1
	v_cndmask_b32_e32 v36, v59, v36, vcc
	v_div_scale_f32 v59, s[20:21], v36, v36, 1.0
	v_rcp_f32_e32 v86, v59
	v_div_scale_f32 v67, vcc, 1.0, v36, 1.0
	v_fma_f32 v87, -v59, v86, 1.0
	v_fmac_f32_e32 v86, v87, v86
	v_mul_f32_e32 v87, v67, v86
	v_fma_f32 v88, -v59, v87, v67
	v_fmac_f32_e32 v87, v88, v86
	v_fma_f32 v59, -v59, v87, v67
	v_div_fmas_f32 v59, v59, v86, v87
	v_div_fixup_f32 v36, v59, v36, 1.0
	v_pk_mul_f32 v[60:61], v[36:37], v[60:61] op_sel_hi:[0,1]
; #define GAS __attribute__((address_space(1)))
; #define LAS __attribute__((address_space(3)))
; __device__ __forceinline__ unsigned pk2(float lo, float hi) { return pg8::cvt_pk_bf16(lo, hi); }
; template <int LO, int HI> __global__ void __launch_bounds__(NWAVES * 64, 2) fox_fwd(Args args) {
;     ...
;             for (int j = 0; j < 4; ++j) v[j] = v[j] * rstd * gm[j] + sh[j];
; #pragma unroll
;             for (int j = 0; j < 2; ++j) { v4u o; o.x = pk2(v[2 * j][0], v[2 * j][1]); o.y = pk2(v[2 * j][2], v[2 * j][3]); o.z = pk2(v[2 * j + 1][0], v[2 * j + 1][1]); o.w = pk2(v[2 * j + 1][2], v[2 * j + 1][3]);
;                 *(GAS v4u*)(HB + (size_t)m * D + 8 * lane + 512 * j) = o; }
;             float fl[8];
; #pragma unroll
;             for (int q = 0; q < 8; ++q) { float a = 0.f;
; #pragma unroll
;                 for (int j = 0; j < 4; ++j) { const f32x4 w = *(const LAS f32x4*)(wf + q * 1024 + P1COL(j)); a += (v[j][0] * w[0] + v[j][1] * w[1]) + (v[j][2] * w[2] + v[j][3] * w[3]); }
;                 fl[q] = wave_sum(a); }
	v_pk_mul_f32 v[62:63], v[36:37], v[62:63] op_sel_hi:[0,1]
	v_pk_mul_f32 v[74:75], v[36:37], v[74:75] op_sel_hi:[0,1]
	v_pk_mul_f32 v[76:77], v[36:37], v[76:77] op_sel_hi:[0,1]
	v_pk_mul_f32 v[82:83], v[36:37], v[82:83] op_sel_hi:[0,1]
	v_pk_mul_f32 v[84:85], v[36:37], v[84:85] op_sel_hi:[0,1]
	v_pk_mul_f32 v[78:79], v[36:37], v[78:79] op_sel_hi:[0,1]
	v_pk_mul_f32 v[80:81], v[36:37], v[80:81] op_sel_hi:[0,1]
	v_pk_fma_f32 v[162:163], v[38:39], v[62:63], v[8:9]
	v_pk_fma_f32 v[214:215], v[40:41], v[60:61], v[6:7]
	v_pk_fma_f32 v[216:217], v[42:43], v[76:77], v[4:5]
	v_pk_fma_f32 v[218:219], v[44:45], v[74:75], v[2:3]
	v_cvt_pk_bf16_f32 v74, v214, v215
	v_cvt_pk_bf16_f32 v75, v162, v163
	v_pk_fma_f32 v[60:61], v[46:47], v[84:85], v[16:17]
	v_cvt_pk_bf16_f32 v76, v218, v219
	v_cvt_pk_bf16_f32 v77, v216, v217
	v_pk_fma_f32 v[62:63], v[48:49], v[82:83], v[14:15]
	v_pk_fma_f32 v[220:221], v[50:51], v[80:81], v[12:13]
	v_pk_fma_f32 v[222:223], v[52:53], v[78:79], v[10:11]
	global_store_dwordx4 v[56:57], v[74:77], off offset:-1024
	s_nop 1
	v_cvt_pk_bf16_f32 v74, v62, v63
	v_cvt_pk_bf16_f32 v75, v60, v61
	v_cvt_pk_bf16_f32 v76, v222, v223
	v_cvt_pk_bf16_f32 v77, v220, v221
	s_nop 0
	global_store_dwordx4 v[56:57], v[74:77], off
	v_mul_f32_e32 v36, v214, v100
	v_mul_f32_e32 v59, v214, v116
	v_mul_f32_e32 v67, v214, v132
	v_mul_f32_e32 v74, v214, v148
	v_mul_f32_e32 v75, v214, v174
	v_mul_f32_e32 v76, v214, v190
	v_mul_f32_e32 v77, v214, v206
	v_mul_f32_e32 v250, v214, v234
	v_fmac_f32_e32 v36, v215, v101
	v_fmac_f32_e32 v59, v215, v117
	v_fmac_f32_e32 v67, v215, v133
	v_fmac_f32_e32 v74, v215, v149
	v_fmac_f32_e32 v75, v215, v175
	v_fmac_f32_e32 v76, v215, v191
	v_fmac_f32_e32 v77, v215, v207
	v_fmac_f32_e32 v250, v215, v235
	v_fmac_f32_e32 v36, v162, v102
	v_fmac_f32_e32 v59, v162, v118
	v_fmac_f32_e32 v67, v162, v134
	v_fmac_f32_e32 v74, v162, v150
	v_fmac_f32_e32 v75, v162, v176
	v_fmac_f32_e32 v76, v162, v192
	v_fmac_f32_e32 v77, v162, v208
	v_fmac_f32_e32 v250, v162, v236
	v_fmac_f32_e32 v36, v163, v103
	v_fmac_f32_e32 v59, v163, v119
	v_fmac_f32_e32 v67, v163, v135
	v_fmac_f32_e32 v74, v163, v151
	v_fmac_f32_e32 v75, v163, v177
	v_fmac_f32_e32 v76, v163, v193
	v_fmac_f32_e32 v77, v163, v209
	v_fmac_f32_e32 v250, v163, v237
	v_fmac_f32_e32 v36, v218, v104
	v_fmac_f32_e32 v59, v218, v120
	v_fmac_f32_e32 v67, v218, v136
	v_fmac_f32_e32 v74, v218, v152
	v_fmac_f32_e32 v75, v218, v178
	v_fmac_f32_e32 v76, v218, v194
	v_fmac_f32_e32 v77, v218, v210
	v_fmac_f32_e32 v250, v218, v238
	v_fmac_f32_e32 v36, v219, v105
	v_fmac_f32_e32 v59, v219, v121
	v_fmac_f32_e32 v67, v219, v137
	v_fmac_f32_e32 v74, v219, v153
	v_fmac_f32_e32 v75, v219, v179
	v_fmac_f32_e32 v76, v219, v195
	v_fmac_f32_e32 v77, v219, v211
	v_fmac_f32_e32 v250, v219, v239
	v_fmac_f32_e32 v36, v216, v106
	v_fmac_f32_e32 v59, v216, v122
	v_fmac_f32_e32 v67, v216, v138
	v_fmac_f32_e32 v74, v216, v154
	v_fmac_f32_e32 v75, v216, v180
	v_fmac_f32_e32 v76, v216, v196
	v_fmac_f32_e32 v77, v216, v212
	v_fmac_f32_e32 v250, v216, v240
	v_fmac_f32_e32 v36, v217, v107
	v_fmac_f32_e32 v59, v217, v123
	v_fmac_f32_e32 v67, v217, v139
	v_fmac_f32_e32 v74, v217, v155
	v_fmac_f32_e32 v75, v217, v181
	v_fmac_f32_e32 v76, v217, v197
	v_fmac_f32_e32 v77, v217, v213
	v_fmac_f32_e32 v250, v217, v241
	v_fmac_f32_e32 v36, v62, v108
	v_fmac_f32_e32 v59, v62, v124
	v_fmac_f32_e32 v67, v62, v140
	v_fmac_f32_e32 v74, v62, v156
	v_fmac_f32_e32 v75, v62, v182
	v_fmac_f32_e32 v76, v62, v198
	v_fmac_f32_e32 v77, v62, v226
	v_fmac_f32_e32 v250, v62, v242
	v_fmac_f32_e32 v36, v63, v109
	v_fmac_f32_e32 v59, v63, v125
	v_fmac_f32_e32 v67, v63, v141
	v_fmac_f32_e32 v74, v63, v157
	v_fmac_f32_e32 v75, v63, v183
	v_fmac_f32_e32 v76, v63, v199
	v_fmac_f32_e32 v77, v63, v227
	v_fmac_f32_e32 v250, v63, v243
	v_fmac_f32_e32 v36, v60, v110
	v_fmac_f32_e32 v59, v60, v126
	v_fmac_f32_e32 v67, v60, v142
	v_fmac_f32_e32 v74, v60, v158
	v_fmac_f32_e32 v75, v60, v184
	v_fmac_f32_e32 v76, v60, v200
	v_fmac_f32_e32 v77, v60, v228
	v_fmac_f32_e32 v250, v60, v244
	v_fmac_f32_e32 v36, v61, v111
	v_fmac_f32_e32 v59, v61, v127
	v_fmac_f32_e32 v67, v61, v143
	v_fmac_f32_e32 v74, v61, v159
	v_fmac_f32_e32 v75, v61, v185
	v_fmac_f32_e32 v76, v61, v201
	v_fmac_f32_e32 v77, v61, v229
	v_fmac_f32_e32 v250, v61, v245
	v_fmac_f32_e32 v36, v222, v112
	v_fmac_f32_e32 v59, v222, v128
	v_fmac_f32_e32 v67, v222, v144
	v_fmac_f32_e32 v74, v222, v170
	v_fmac_f32_e32 v75, v222, v186
	v_fmac_f32_e32 v76, v222, v202
	v_fmac_f32_e32 v77, v222, v230
	v_fmac_f32_e32 v250, v222, v246
	v_fmac_f32_e32 v36, v223, v113
	v_fmac_f32_e32 v59, v223, v129
	v_fmac_f32_e32 v67, v223, v145
	v_fmac_f32_e32 v74, v223, v171
	v_fmac_f32_e32 v75, v223, v187
	v_fmac_f32_e32 v76, v223, v203
	v_fmac_f32_e32 v77, v223, v231
	v_fmac_f32_e32 v250, v223, v247
	v_fmac_f32_e32 v36, v220, v114
	v_fmac_f32_e32 v59, v220, v130
	v_fmac_f32_e32 v67, v220, v146
	v_fmac_f32_e32 v74, v220, v172
	v_fmac_f32_e32 v75, v220, v188
	v_fmac_f32_e32 v76, v220, v204
	v_fmac_f32_e32 v77, v220, v232
	v_fmac_f32_e32 v250, v220, v248
	v_fmac_f32_e32 v36, v221, v115
	v_fmac_f32_e32 v59, v221, v131
	v_fmac_f32_e32 v67, v221, v147
	v_fmac_f32_e32 v74, v221, v173
	v_fmac_f32_e32 v75, v221, v189
	v_fmac_f32_e32 v76, v221, v205
	v_fmac_f32_e32 v77, v221, v233
	v_fmac_f32_e32 v250, v221, v249
	v_mov_b32_e32 v60, v250
	v_mov_b32_e32 v61, 0
	s_waitcnt lgkmcnt(0)
; template <int LO, int HI> __global__ void __launch_bounds__(NWAVES * 64, 2) fox_fwd(Args args) {
;     ...
;                 fl[q] = wave_sum(a); }
;             float mine = fl[0];
; #pragma unroll
;             for (int q = 1; q < 8; ++q) mine = (lane == q) ? fl[q] : mine;
;             { const float z = mine + bfv; const float ls = fminf(z, 0.f) - log1pf(__expf(-fabsf(z)));
	v_add_f32_e32 v60, v60, v61
	v_add_f32_dpp v62, v36, v36 quad_perm:[1,0,3,2] row_mask:0xf bank_mask:0xf
	v_add_f32_dpp v63, v59, v59 quad_perm:[1,0,3,2] row_mask:0xf bank_mask:0xf
	v_add_f32_dpp v78, v67, v67 quad_perm:[1,0,3,2] row_mask:0xf bank_mask:0xf
	v_add_f32_dpp v79, v74, v74 quad_perm:[1,0,3,2] row_mask:0xf bank_mask:0xf
	v_add_f32_dpp v80, v75, v75 quad_perm:[1,0,3,2] row_mask:0xf bank_mask:0xf
	v_add_f32_dpp v81, v76, v76 quad_perm:[1,0,3,2] row_mask:0xf bank_mask:0xf
	v_add_f32_dpp v82, v77, v77 quad_perm:[1,0,3,2] row_mask:0xf bank_mask:0xf
	v_add_f32_dpp v61, v60, v60 quad_perm:[1,0,3,2] row_mask:0xf bank_mask:0xf
	v_add_f32_dpp v36, v62, v62 quad_perm:[2,3,0,1] row_mask:0xf bank_mask:0xf
	v_add_f32_dpp v59, v63, v63 quad_perm:[2,3,0,1] row_mask:0xf bank_mask:0xf
	v_add_f32_dpp v67, v78, v78 quad_perm:[2,3,0,1] row_mask:0xf bank_mask:0xf
	v_add_f32_dpp v74, v79, v79 quad_perm:[2,3,0,1] row_mask:0xf bank_mask:0xf
	v_add_f32_dpp v75, v80, v80 quad_perm:[2,3,0,1] row_mask:0xf bank_mask:0xf
	v_add_f32_dpp v76, v81, v81 quad_perm:[2,3,0,1] row_mask:0xf bank_mask:0xf
	v_add_f32_dpp v77, v82, v82 quad_perm:[2,3,0,1] row_mask:0xf bank_mask:0xf
	v_add_f32_dpp v60, v61, v61 quad_perm:[2,3,0,1] row_mask:0xf bank_mask:0xf
	v_add_f32_dpp v62, v36, v36 row_half_mirror row_mask:0xf bank_mask:0xf
	v_add_f32_dpp v63, v59, v59 row_half_mirror row_mask:0xf bank_mask:0xf
	v_add_f32_dpp v78, v67, v67 row_half_mirror row_mask:0xf bank_mask:0xf
	v_add_f32_dpp v79, v74, v74 row_half_mirror row_mask:0xf bank_mask:0xf
	v_add_f32_dpp v80, v75, v75 row_half_mirror row_mask:0xf bank_mask:0xf
	v_add_f32_dpp v81, v76, v76 row_half_mirror row_mask:0xf bank_mask:0xf
	v_add_f32_dpp v82, v77, v77 row_half_mirror row_mask:0xf bank_mask:0xf
	v_add_f32_dpp v61, v60, v60 row_half_mirror row_mask:0xf bank_mask:0xf
	v_add_f32_dpp v36, v62, v62 row_mirror row_mask:0xf bank_mask:0xf
	v_add_f32_dpp v59, v63, v63 row_mirror row_mask:0xf bank_mask:0xf
	v_add_f32_dpp v67, v78, v78 row_mirror row_mask:0xf bank_mask:0xf
	v_add_f32_dpp v74, v79, v79 row_mirror row_mask:0xf bank_mask:0xf
	v_add_f32_dpp v75, v80, v80 row_mirror row_mask:0xf bank_mask:0xf
	v_add_f32_dpp v76, v81, v81 row_mirror row_mask:0xf bank_mask:0xf
	v_add_f32_dpp v77, v82, v82 row_mirror row_mask:0xf bank_mask:0xf
	v_add_f32_dpp v60, v61, v61 row_mirror row_mask:0xf bank_mask:0xf
	v_mov_b32_e32 v62, v36
	v_mov_b32_e32 v63, v59
	v_mov_b32_e32 v78, v67
	v_mov_b32_e32 v79, v74
	v_mov_b32_e32 v80, v75
	v_mov_b32_e32 v81, v76
	v_mov_b32_e32 v82, v77
	v_mov_b32_e32 v61, v60
	v_permlane16_swap_b32_e32 v62, v36
	v_permlane16_swap_b32_e32 v63, v59
	v_permlane16_swap_b32_e32 v78, v67
	v_permlane16_swap_b32_e32 v79, v74
	v_permlane16_swap_b32_e32 v80, v75
	v_permlane16_swap_b32_e32 v81, v76
	v_permlane16_swap_b32_e32 v82, v77
	v_permlane16_swap_b32_e32 v61, v60
	v_add_f32_e32 v62, v62, v36
	v_add_f32_e32 v63, v63, v59
	v_add_f32_e32 v78, v78, v67
	v_add_f32_e32 v79, v79, v74
	v_add_f32_e32 v80, v80, v75
	v_add_f32_e32 v81, v81, v76
	v_add_f32_e32 v82, v82, v77
	v_add_f32_e32 v61, v61, v60
	v_mov_b32_e32 v36, v62
	v_mov_b32_e32 v59, v63
	v_mov_b32_e32 v67, v78
	v_mov_b32_e32 v74, v79
	v_mov_b32_e32 v75, v80
	v_mov_b32_e32 v76, v81
	v_mov_b32_e32 v77, v82
	v_mov_b32_e32 v60, v61
	v_permlane32_swap_b32_e32 v36, v62
	v_permlane32_swap_b32_e32 v59, v63
	v_permlane32_swap_b32_e32 v67, v78
	v_permlane32_swap_b32_e32 v74, v79
	v_permlane32_swap_b32_e32 v75, v80
	v_permlane32_swap_b32_e32 v76, v81
	v_permlane32_swap_b32_e32 v77, v82
	v_permlane32_swap_b32_e32 v60, v61
	v_add_f32_e32 v36, v36, v62
	v_add_f32_e32 v59, v59, v63
	v_add_f32_e32 v62, v67, v78
	v_add_f32_e32 v63, v74, v79
	v_add_f32_e32 v67, v75, v80
	v_add_f32_e32 v74, v76, v81
	v_add_f32_e32 v75, v77, v82
	v_add_f32_e32 v60, v60, v61
	v_cndmask_b32_e64 v36, v36, v59, s[4:5]
	v_cndmask_b32_e64 v36, v36, v62, s[6:7]
	v_cndmask_b32_e64 v36, v36, v63, s[8:9]
	v_cndmask_b32_e64 v36, v36, v67, s[10:11]
	v_cndmask_b32_e64 v36, v36, v74, s[12:13]
	v_cndmask_b32_e64 v36, v36, v75, s[14:15]
	v_cndmask_b32_e64 v36, v36, v60, s[16:17]
	v_add_f32_e32 v36, v71, v36
	v_min_f32_e32 v67, 0, v36
	v_mul_f32_e64 v36, |v36|, s29
	v_exp_f32_e32 v36, v36
	v_lshl_add_u64 v[56:57], v[56:57], 0, s[40:41]
	v_add_f32_e32 v59, 1.0, v36
	v_add_f32_e32 v62, -1.0, v59
	v_frexp_mant_f32_e32 v63, v59
	v_cvt_f64_f32_e32 v[60:61], v59
	v_sub_f32_e32 v74, v62, v59
	v_frexp_exp_i32_f64_e32 v60, v[60:61]
	v_cmp_gt_f32_e32 vcc, s37, v63
	v_sub_f32_e32 v62, v36, v62
	v_add_f32_e32 v61, 1.0, v74
	v_subbrev_co_u32_e32 v60, vcc, 0, v60, vcc
	v_add_f32_e32 v61, v62, v61
	v_sub_u32_e32 v62, 0, v60
	v_ldexp_f32 v59, v59, v62
	v_ldexp_f32 v61, v61, v62
	v_add_f32_e32 v62, -1.0, v59
	v_add_f32_e32 v74, 1.0, v59
	v_add_f32_e32 v63, 1.0, v62
	v_add_f32_e32 v75, -1.0, v74
	v_sub_f32_e32 v63, v59, v63
	v_sub_f32_e32 v59, v59, v75
	v_add_f32_e32 v59, v61, v59
	v_add_f32_e32 v75, v61, v63
	v_add_f32_e32 v61, v74, v59
	v_rcp_f32_e32 v78, v61
	v_add_f32_e32 v63, v62, v75
	v_sub_f32_e32 v74, v61, v74
	v_sub_f32_e32 v59, v59, v74
	v_mul_f32_e32 v80, v63, v78
	v_mul_f32_e32 v74, v61, v80
	v_fma_f32 v76, v80, v61, -v74
	v_sub_f32_e32 v62, v63, v62
	v_fmac_f32_e32 v76, v80, v59
	v_sub_f32_e32 v79, v75, v62
	v_add_f32_e32 v62, v74, v76
; template <int LO, int HI> __global__ void __launch_bounds__(NWAVES * 64, 2) fox_fwd(Args args) {
;     ...
;             { const float z = mine + bfv; const float ls = fminf(z, 0.f) - log1pf(__expf(-fabsf(z)));
; #pragma unroll
;               for (int k = 0; k < 4; ++k)
; #pragma unroll
;                   for (int e = 0; e < 4; ++e) lsq[k][e] = (r == 4 * k + e) ? ls : lsq[k][e]; }
;         }
;         if (lane < 8) { f32x4* dst = (f32x4*)(LF + (size_t)(b * 8 + lane) * T + (m0 - b * T));
; #pragma unroll
;             for (int k = 0; k < 4; ++k) dst[k] = lsq[k]; }
	v_sub_f32_e32 v75, v63, v62
	v_mov_b32_e32 v77, v62
	v_pk_add_f32 v[62:63], v[62:63], v[74:75] neg_lo:[0,1] neg_hi:[0,1]
	v_cvt_f32_i32_e32 v60, v60
	v_pk_add_f32 v[62:63], v[62:63], v[76:77] neg_lo:[0,1] neg_hi:[0,1]
	v_cmp_neq_f32_e32 vcc, s46, v36
	v_add_f32_e32 v63, v79, v63
	v_add_f32_e32 v62, v62, v63
	v_add_f32_e32 v63, v75, v62
	v_mul_f32_e32 v77, v78, v63
	v_mul_f32_e32 v74, v61, v77
	v_fma_f32 v76, v77, v61, -v74
	v_sub_f32_e32 v75, v75, v63
	v_fmac_f32_e32 v76, v77, v59
	v_add_f32_e32 v79, v62, v75
	v_add_f32_e32 v81, v80, v77
	v_add_f32_e32 v62, v74, v76
	v_sub_f32_e32 v61, v81, v80
	v_sub_f32_e32 v75, v63, v62
	v_sub_f32_e32 v59, v77, v61
	v_mov_b32_e32 v77, v62
	v_pk_add_f32 v[62:63], v[62:63], v[74:75] neg_lo:[0,1] neg_hi:[0,1]
	s_nop 0
	v_pk_add_f32 v[62:63], v[62:63], v[76:77] neg_lo:[0,1] neg_hi:[0,1]
	s_nop 0
	v_add_f32_e32 v61, v79, v63
	v_add_f32_e32 v61, v62, v61
	v_add_f32_e32 v61, v75, v61
	v_mul_f32_e32 v61, v78, v61
	v_add_f32_e32 v59, v59, v61
	v_add_f32_e32 v61, v81, v59
	v_mul_f32_e32 v62, v61, v61
	v_sub_f32_e32 v74, v61, v81
	v_fmamk_f32 v75, v62, 0x3e9b6dac, v20
	v_ldexp_f32 v63, v61, 1
	v_sub_f32_e32 v74, v59, v74
	v_mul_f32_e32 v61, v61, v62
	v_fmaak_f32 v59, v62, v75, 0x3f2aaada
	v_ldexp_f32 v77, v74, 1
	v_pk_mul_f32 v[74:75], v[60:61], v[58:59]
	s_nop 0
	v_fma_f32 v62, v60, s36, -v74
	v_fmac_f32_e32 v62, 0xb102e308, v60
	v_pk_add_f32 v[60:61], v[74:75], v[62:63]
	v_mov_b32_e32 v76, v74
	v_sub_f32_e32 v59, v61, v63
	v_sub_f32_e32 v59, v75, v59
	v_add_f32_e32 v77, v77, v59
	v_pk_add_f32 v[78:79], v[60:61], v[74:75] neg_lo:[0,1] neg_hi:[0,1]
	v_pk_add_f32 v[74:75], v[60:61], v[76:77]
	v_mov_b32_e32 v63, v60
	v_mov_b32_e32 v79, v75
	v_pk_add_f32 v[82:83], v[62:63], v[78:79] neg_lo:[0,1] neg_hi:[0,1]
	v_pk_add_f32 v[62:63], v[62:63], v[78:79]
	v_mov_b32_e32 v81, v60
	v_pk_add_f32 v[78:79], v[62:63], v[60:61] op_sel:[1,0] op_sel_hi:[0,1] neg_lo:[0,1] neg_hi:[0,1]
	v_mov_b32_e32 v80, v77
	v_mov_b32_e32 v76, v75
	v_mov_b32_e32 v77, v63
	v_pk_mov_b32 v[60:61], v[60:61], v[78:79] op_sel:[1,0]
	v_pk_add_f32 v[74:75], v[74:75], v[78:79] op_sel_hi:[1,0] neg_lo:[0,1] neg_hi:[0,1]
	v_pk_add_f32 v[60:61], v[76:77], v[60:61] neg_lo:[0,1] neg_hi:[0,1]
	v_mov_b32_e32 v74, v82
	v_pk_add_f32 v[60:61], v[80:81], v[60:61] neg_lo:[0,1] neg_hi:[0,1]
	v_mov_b32_e32 v83, v63
	v_pk_add_f32 v[74:75], v[74:75], v[60:61]
	s_nop 0
	v_pk_add_f32 v[76:77], v[74:75], v[74:75] op_sel:[0,1] op_sel_hi:[1,0]
	s_nop 0
	v_pk_add_f32 v[62:63], v[62:63], v[76:77] op_sel:[1,0] op_sel_hi:[0,1]
	v_mov_b32_e32 v75, v62
	v_mov_b32_e32 v61, v76
	v_pk_add_f32 v[76:77], v[74:75], v[82:83] neg_lo:[0,1] neg_hi:[0,1]
	s_nop 0
	v_sub_f32_e32 v59, v74, v76
	v_pk_add_f32 v[60:61], v[60:61], v[76:77] neg_lo:[0,1] neg_hi:[0,1]
	v_sub_f32_e32 v59, v82, v59
	v_add_f32_e32 v59, v60, v59
	v_add_f32_e32 v59, v59, v61
	v_add_f32_e32 v59, v62, v59
	v_cndmask_b32_e32 v59, v64, v59, vcc
	v_cmp_ngt_f32_e32 vcc, -1.0, v36
	s_nop 1
	v_cndmask_b32_e32 v59, v65, v59, vcc
	v_cmp_neq_f32_e32 vcc, -1.0, v36
	s_nop 1
	v_cndmask_b32_e32 v59, v66, v59, vcc
	v_cmp_lt_f32_e64 vcc, |v36|, s47
	s_nop 1
	v_cndmask_b32_e32 v36, v59, v36, vcc
	v_sub_f32_e32 v36, v67, v36
	s_cselect_b64 vcc, -1, 0
	s_cmpk_eq_i32 s30, 0x1000
	v_cndmask_b32_e32 v37, v37, v36, vcc
	s_cselect_b64 vcc, -1, 0
	s_cmpk_eq_i32 s30, 0x2000
	v_cndmask_b32_e32 v21, v21, v36, vcc
	s_cselect_b64 vcc, -1, 0
	s_cmpk_eq_i32 s30, 0x3000
	v_cndmask_b32_e32 v30, v30, v36, vcc
	s_cselect_b64 vcc, -1, 0
	s_cmpk_eq_i32 s30, 0x4000
	v_cndmask_b32_e32 v31, v31, v36, vcc
	s_cselect_b64 vcc, -1, 0
	s_cmpk_eq_i32 s30, 0x5000
	v_cndmask_b32_e32 v32, v32, v36, vcc
	s_cselect_b64 vcc, -1, 0
	s_cmpk_eq_i32 s30, 0x6000
	v_cndmask_b32_e32 v33, v33, v36, vcc
	s_cselect_b64 vcc, -1, 0
	s_cmpk_eq_i32 s30, 0x7000
	v_cndmask_b32_e32 v26, v26, v36, vcc
	s_cselect_b64 vcc, -1, 0
	s_cmpk_eq_u32 s30, 0x8000
	v_cndmask_b32_e32 v27, v27, v36, vcc
	s_cselect_b64 vcc, -1, 0
	s_cmpk_eq_u32 s30, 0x9000
	v_cndmask_b32_e32 v28, v28, v36, vcc
	s_cselect_b64 vcc, -1, 0
	s_cmpk_eq_u32 s30, 0xa000
	v_cndmask_b32_e32 v29, v29, v36, vcc
	s_cselect_b64 vcc, -1, 0
	s_cmpk_eq_u32 s30, 0xb000
	v_cndmask_b32_e32 v22, v22, v36, vcc
	s_cselect_b64 vcc, -1, 0
	s_cmpk_eq_u32 s30, 0xc000
	v_cndmask_b32_e32 v23, v23, v36, vcc
	s_cselect_b64 vcc, -1, 0
	s_cmpk_eq_u32 s30, 0xd000
	v_cndmask_b32_e32 v24, v24, v36, vcc
	s_cselect_b64 vcc, -1, 0
	s_add_u32 s30, s30, 0x1000
	s_addc_u32 s31, s31, 0
	s_cmpk_eq_u32 s30, 0xe000
	v_cndmask_b32_e32 v25, v25, v36, vcc
	s_cbranch_scc0 .LBB0_131
	v_cmp_gt_u32_e32 vcc, 8, v1
	s_and_saveexec_b64 s[4:5], vcc
	s_cbranch_execz .LBB0_134
	v_lshl_or_b32 v2, s44, 3, v1
	v_ashrrev_i32_e32 v3, 31, v2
	s_lshl_b32 s6, s44, 12
	v_lshlrev_b64 v[2:3], 14, v[2:3]
	s_sub_i32 s6, s28, s6
	v_lshl_add_u64 v[2:3], s[26:27], 0, v[2:3]
	s_ashr_i32 s7, s6, 31
	v_lshl_add_u64 v[2:3], s[6:7], 2, v[2:3]
	s_mov_b64 s[6:7], 0x100000
	v_lshl_add_u64 v[4:5], v[2:3], 0, s[6:7]
	v_add_co_u32_e32 v2, vcc, 0x100000, v2
	v_mov_b32_e32 v20, v37
	s_nop 0
	v_addc_co_u32_e32 v3, vcc, 0, v3, vcc
	global_store_dwordx4 v[2:3], v[18:21], off
	global_store_dwordx4 v[4:5], v[30:33], off offset:16
	global_store_dwordx4 v[4:5], v[26:29], off offset:32
	global_store_dwordx4 v[4:5], v[22:25], off offset:48
